# RESID epilogues: the eight sum-of-squares cross-lane reductions batched after the last step (2 LDS waits instead of 16); diff and MLA loop back edges rotated
# baseline (speedup 1.0000x reference)
; DI void attn_diff_unit(const Params& p, int li, int b, int h, int qb, char* smem, bool pre, int nh, bool has_next) {
;     ...
;     if (kt + 1 < 32) put_stage(smem + ((kt + 1) & 1) * STG);
;     else if (has_next) put_stage(smem);
;     __syncthreads();
;     if (kt + 2 < 32) get_stage(kt + 2);
;     else if (kt == 30 && has_next) { gk += (nh - h) * 128; gv += (nh - h) * 128; get_stage(0); }
.LBB0_592:
	s_addk_i32 s24, 0x80
	s_add_u32 s34, s34, 0x40000
	s_addc_u32 s35, s35, 0
	s_mov_b32 s43, s44
	s_xor_b32 s45, s45, 0x12800
	s_cmpk_lg_i32 s24, 0x1000
	s_cbranch_scc1 .LBB0_568

; DI bool softmax_tile(f32x16& s0, f32x16& s1, float& m, float& l, float& alpha, bf16x8* pf, int lane, bool first, bool check) {
;     ...
;   for (int i = 0; i < 16; ++i) { s0[i] = __builtin_amdgcn_exp2f(s0[i]); sum += s0[i]; }
; #pragma unroll
;   for (int i = 0; i < 16; ++i) { s1[i] = __builtin_amdgcn_exp2f(s1[i]); sum += s1[i]; }
;   l += sum;
; DI void attn_mla_unit(const Params& p, int b, int h, int qb, char* smem, bool pre, int nh, bool has_next) {
;     ...
;     if (kt + 2 < 32) get_stage(kt + 2);
;     else if (kt == 30 && has_next) { gk += (nh - h) * 64; gv += (nh - h) * 64; get_stage(0); }
.LBB0_1495:
	v_add_f32_e32 v48, v49, v48
	v_add_f32_e32 v48, v50, v48
	v_add_f32_e32 v48, v51, v48
	v_add_f32_e32 v48, v52, v48
	v_add_f32_e32 v48, v53, v48
	v_add_f32_e32 v48, v54, v48
	v_add_f32_e32 v48, v55, v48
	v_add_f32_e32 v48, v56, v48
	v_add_f32_e32 v48, v57, v48
	v_add_f32_e32 v48, v58, v48
	v_add_f32_e32 v48, v59, v48
	v_add_f32_e32 v48, v60, v48
	v_add_f32_e32 v48, v61, v48
	v_add_f32_e32 v48, v62, v48
	v_add_f32_e32 v48, v63, v48
	v_add_f32_e32 v48, v67, v48
	v_add_f32_e32 v48, v69, v48
	v_add_f32_e32 v48, v70, v48
	v_add_f32_e32 v48, v71, v48
	v_add_f32_e32 v36, v36, v48
	v_add_f32_e32 v36, v37, v36
	v_add_f32_e32 v36, v38, v36
	v_add_f32_e32 v36, v39, v36
	v_add_f32_e32 v36, v40, v36
	v_add_f32_e32 v36, v41, v36
	v_add_f32_e32 v36, v42, v36
	v_add_f32_e32 v36, v43, v36
	v_add_f32_e32 v36, v44, v36
	v_add_f32_e32 v36, v45, v36
	v_add_f32_e32 v36, v46, v36
	s_add_u32 s12, s12, 0x20000
	v_add_f32_e32 v36, v47, v36
	s_addc_u32 s13, s13, 0
	s_add_i32 s18, s18, 1
	s_mov_b64 s[16:17], 0x2000
	v_add_f32_e32 v153, v66, v36
	s_cmp_lg_u32 s12, 0x430000
	v_lshl_add_u64 v[64:65], v[64:65], 0, s[16:17]
	v_mov_b64_e32 v[128:129], v[32:33]
	v_mov_b64_e32 v[130:131], v[34:35]
	s_cbranch_scc1 .LBB0_1482

; DI float bf2f(unsigned v) { return __uint_as_float(v << 16); }
;   DI void operator()(const f32x4 (&acc)[2][2][4][2], const pg8::Unit& u, int wr, int wc, int fr_, int fq_) const {
;     ...
;             } else if (EPI == EPI_RESID) {
;               if (n == 0) {
;                 const int f8 = u.pn * 256 + bj * 128 + wc * 32 + 8 * fq;
;                 const f32x4 v1 = acc[ai][bj][m][1];
;                 f32x4 r0, r1;
;                 if (rsrc) {
;                   r0 = *(const f32x4*)(rsrc + (size_t)token * 1024 + f8); r1 = *(const f32x4*)(rsrc + (size_t)token * 1024 + f8 + 4);
;                 } else {
;                   const u32x4 xu = *(const u32x4*)(xr + (size_t)token * 1024 + f8);
;                   r0 = (f32x4){bf2f(xu.x & 0xffffu), bf2f(xu.x >> 16), bf2f(xu.y & 0xffffu), bf2f(xu.y >> 16)};
;                   r1 = (f32x4){bf2f(xu.z & 0xffffu), bf2f(xu.z >> 16), bf2f(xu.w & 0xffffu), bf2f(xu.w >> 16)};
;                 }
;                 r0 += v; r1 += v1;
;                 st_bf8(xr + (size_t)token * 1024 + f8, r0, r1, 1.f);
;                 ssq += r0[0] * r0[0] + r0[1] * r0[1] + r0[2] * r0[2] + r0[3] * r0[3] + r1[0] * r1[0] + r1[1] * r1[1] + r1[2] * r1[2] + r1[3] * r1[3];
;               }
;             } else {
;               if (n == 0) {
;                 const f32x4 v1 = acc[ai][bj][m][1];
;                 u32x4 o4;
;                 { const float t0 = fmaxf(v[0], 0.f) * rinv, t1 = fmaxf(v[1], 0.f) * rinv, t2 = fmaxf(v[2], 0.f) * rinv, t3 = fmaxf(v[3], 0.f) * rinv;
;                   o4.x = pack2(t0 * t0, t1 * t1); o4.y = pack2(t2 * t2, t3 * t3); }
;                 { const float t0 = fmaxf(v1[0], 0.f) * rinv, t1 = fmaxf(v1[1], 0.f) * rinv, t2 = fmaxf(v1[2], 0.f) * rinv, t3 = fmaxf(v1[3], 0.f) * rinv;
;                   o4.z = pack2(t0 * t0, t1 * t1); o4.w = pack2(t2 * t2, t3 * t3); }
;                 *(u32x4*)((u16*)big + (size_t)token * 4096 + u.pn * 256 + bj * 128 + wc * 32 + 8 * fq) = o4;
;               }
;             }
;           }
;         if (EPI == EPI_RESID) {
;           ssq += shx(ssq, 16, t_ & 63);
;           ssq += shx(ssq, 32, t_ & 63);
;           if (fq == 0) ss_out[(size_t)token * 16 + u.pn * 4 + wc] = ssq;
.LBB0_1653:
	v_pk_add_f32 v[116:117], v[116:117], v[120:121]
	v_mul_f32_e32 v134, v157, v157
	v_pk_add_f32 v[118:119], v[118:119], v[122:123]
	v_pk_add_f32 v[122:123], v[112:113], v[124:125]
	v_mul_f32_e32 v112, v117, v117
	v_fmac_f32_e32 v134, v156, v156
	v_fmac_f32_e32 v112, v116, v116
	v_fmac_f32_e32 v134, v130, v130
	v_fmac_f32_e32 v112, v118, v118
	v_fmac_f32_e32 v134, v131, v131
	v_fmac_f32_e32 v112, v119, v119
	v_fmac_f32_e32 v134, v132, v132
	v_fmac_f32_e32 v112, v122, v122
	v_fmac_f32_e32 v134, v133, v133
	v_pk_add_f32 v[120:121], v[114:115], v[126:127]
	v_fmac_f32_e32 v112, v123, v123
	v_fmac_f32_e32 v134, v128, v128
	v_fmac_f32_e32 v112, v120, v120
	v_fmac_f32_e32 v134, v129, v129
	v_lshlrev_b32_e32 v128, 2, v161
	v_fmac_f32_e32 v112, v121, v121
	v_bitop3_b32 v129, v128, 64, v190 bitop3:0x6c
	v_add_f32_e32 v112, v134, v112
	v_mov_b32_e32 v236, v112
	s_movk_i32 s4, 0x80
	v_bitop3_b32 v128, v128, s4, v190 bitop3:0x6c
	s_lshl_b32 s28, s24, 2
	v_cmp_eq_u32_e64 s[4:5], 0, v160
	s_ashr_i32 s29, s28, 31
	v_cvt_pk_bf16_f32 v114, v116, v117
	v_cvt_pk_bf16_f32 v115, v118, v119
	v_cvt_pk_bf16_f32 v116, v122, v123
	v_cvt_pk_bf16_f32 v117, v120, v121
	global_store_dwordx4 v[152:153], v[114:117], off offset:256
	v_or_b32_e32 v120, 16, v150
	v_ashrrev_i32_e32 v121, 31, v120
	s_waitcnt lgkmcnt(0)
	v_lshlrev_b64 v[112:113], 12, v[120:121]
	v_lshl_add_u64 v[112:113], s[6:7], 0, v[112:113]
	s_and_b64 vcc, exec, s[2:3]
	v_lshl_add_u64 v[124:125], v[148:149], 2, v[112:113]
	s_cbranch_vccnz .LBB0_1658
	v_mov_b64_e32 v[116:117], v[196:197]
	v_mov_b64_e32 v[118:119], v[198:199]
	v_mov_b64_e32 v[112:113], v[178:179]
	v_mov_b64_e32 v[114:115], v[180:181]
	s_mov_b64 s[34:35], 0
	s_branch .LBB0_1659

; DI float bf2f(unsigned v) { return __uint_as_float(v << 16); }
;   DI void operator()(const f32x4 (&acc)[2][2][4][2], const pg8::Unit& u, int wr, int wc, int fr_, int fq_) const {
;     ...
;             } else if (EPI == EPI_RESID) {
;               if (n == 0) {
;                 const int f8 = u.pn * 256 + bj * 128 + wc * 32 + 8 * fq;
;                 const f32x4 v1 = acc[ai][bj][m][1];
;                 f32x4 r0, r1;
;                 if (rsrc) {
;                   r0 = *(const f32x4*)(rsrc + (size_t)token * 1024 + f8); r1 = *(const f32x4*)(rsrc + (size_t)token * 1024 + f8 + 4);
;                 } else {
;                   const u32x4 xu = *(const u32x4*)(xr + (size_t)token * 1024 + f8);
;                   r0 = (f32x4){bf2f(xu.x & 0xffffu), bf2f(xu.x >> 16), bf2f(xu.y & 0xffffu), bf2f(xu.y >> 16)};
;                   r1 = (f32x4){bf2f(xu.z & 0xffffu), bf2f(xu.z >> 16), bf2f(xu.w & 0xffffu), bf2f(xu.w >> 16)};
;                 }
;                 r0 += v; r1 += v1;
;                 st_bf8(xr + (size_t)token * 1024 + f8, r0, r1, 1.f);
;                 ssq += r0[0] * r0[0] + r0[1] * r0[1] + r0[2] * r0[2] + r0[3] * r0[3] + r1[0] * r1[0] + r1[1] * r1[1] + r1[2] * r1[2] + r1[3] * r1[3];
;               }
;             } else {
;               if (n == 0) {
;                 const f32x4 v1 = acc[ai][bj][m][1];
;                 u32x4 o4;
;                 { const float t0 = fmaxf(v[0], 0.f) * rinv, t1 = fmaxf(v[1], 0.f) * rinv, t2 = fmaxf(v[2], 0.f) * rinv, t3 = fmaxf(v[3], 0.f) * rinv;
;                   o4.x = pack2(t0 * t0, t1 * t1); o4.y = pack2(t2 * t2, t3 * t3); }
;                 { const float t0 = fmaxf(v1[0], 0.f) * rinv, t1 = fmaxf(v1[1], 0.f) * rinv, t2 = fmaxf(v1[2], 0.f) * rinv, t3 = fmaxf(v1[3], 0.f) * rinv;
;                   o4.z = pack2(t0 * t0, t1 * t1); o4.w = pack2(t2 * t2, t3 * t3); }
;                 *(u32x4*)((u16*)big + (size_t)token * 4096 + u.pn * 256 + bj * 128 + wc * 32 + 8 * fq) = o4;
;               }
;             }
;           }
;         if (EPI == EPI_RESID) {
;           ssq += shx(ssq, 16, t_ & 63);
;           ssq += shx(ssq, 32, t_ & 63);
;           if (fq == 0) ss_out[(size_t)token * 16 + u.pn * 4 + wc] = ssq;
.LBB0_1664:
	v_pk_add_f32 v[100:101], v[100:101], v[104:105]
	v_mul_f32_e32 v118, v127, v127
	v_pk_add_f32 v[102:103], v[102:103], v[106:107]
	v_pk_add_f32 v[106:107], v[96:97], v[108:109]
	v_mul_f32_e32 v96, v101, v101
	v_fmac_f32_e32 v118, v126, v126
	v_fmac_f32_e32 v96, v100, v100
	v_fmac_f32_e32 v118, v114, v114
	v_fmac_f32_e32 v96, v102, v102
	v_fmac_f32_e32 v118, v115, v115
	v_fmac_f32_e32 v96, v103, v103
	v_fmac_f32_e32 v118, v116, v116
	v_fmac_f32_e32 v96, v106, v106
	v_fmac_f32_e32 v118, v117, v117
	v_pk_add_f32 v[104:105], v[98:99], v[110:111]
	v_fmac_f32_e32 v96, v107, v107
	v_fmac_f32_e32 v118, v112, v112
	v_fmac_f32_e32 v96, v104, v104
	v_fmac_f32_e32 v118, v113, v113
	v_fmac_f32_e32 v96, v105, v105
	v_add_f32_e32 v96, v118, v96
	v_mov_b32_e32 v246, v96
	v_cvt_pk_bf16_f32 v98, v100, v101
	v_cvt_pk_bf16_f32 v99, v102, v103
	v_cvt_pk_bf16_f32 v100, v106, v107
	v_cvt_pk_bf16_f32 v101, v104, v105
	global_store_dwordx4 v[122:123], v[98:101], off offset:256
	v_or_b32_e32 v104, 32, v150
	v_ashrrev_i32_e32 v105, 31, v104
	s_waitcnt lgkmcnt(0)
	v_lshlrev_b64 v[96:97], 12, v[104:105]
	v_lshl_add_u64 v[96:97], s[6:7], 0, v[96:97]
	s_and_b64 vcc, exec, s[2:3]
	v_lshl_add_u64 v[108:109], v[148:149], 2, v[96:97]
	s_cbranch_vccnz .LBB0_1669
	v_mov_b64_e32 v[100:101], v[212:213]
	v_mov_b64_e32 v[102:103], v[214:215]
	v_mov_b64_e32 v[96:97], v[208:209]
	v_mov_b64_e32 v[98:99], v[210:211]
	s_mov_b64 s[34:35], 0
	s_branch .LBB0_1670

; DI float bf2f(unsigned v) { return __uint_as_float(v << 16); }
;   DI void operator()(const f32x4 (&acc)[2][2][4][2], const pg8::Unit& u, int wr, int wc, int fr_, int fq_) const {
;     ...
;             } else if (EPI == EPI_RESID) {
;               if (n == 0) {
;                 const int f8 = u.pn * 256 + bj * 128 + wc * 32 + 8 * fq;
;                 const f32x4 v1 = acc[ai][bj][m][1];
;                 f32x4 r0, r1;
;                 if (rsrc) {
;                   r0 = *(const f32x4*)(rsrc + (size_t)token * 1024 + f8); r1 = *(const f32x4*)(rsrc + (size_t)token * 1024 + f8 + 4);
;                 } else {
;                   const u32x4 xu = *(const u32x4*)(xr + (size_t)token * 1024 + f8);
;                   r0 = (f32x4){bf2f(xu.x & 0xffffu), bf2f(xu.x >> 16), bf2f(xu.y & 0xffffu), bf2f(xu.y >> 16)};
;                   r1 = (f32x4){bf2f(xu.z & 0xffffu), bf2f(xu.z >> 16), bf2f(xu.w & 0xffffu), bf2f(xu.w >> 16)};
;                 }
;                 r0 += v; r1 += v1;
;                 st_bf8(xr + (size_t)token * 1024 + f8, r0, r1, 1.f);
;                 ssq += r0[0] * r0[0] + r0[1] * r0[1] + r0[2] * r0[2] + r0[3] * r0[3] + r1[0] * r1[0] + r1[1] * r1[1] + r1[2] * r1[2] + r1[3] * r1[3];
;               }
;             } else {
;               if (n == 0) {
;                 const f32x4 v1 = acc[ai][bj][m][1];
;                 u32x4 o4;
;                 { const float t0 = fmaxf(v[0], 0.f) * rinv, t1 = fmaxf(v[1], 0.f) * rinv, t2 = fmaxf(v[2], 0.f) * rinv, t3 = fmaxf(v[3], 0.f) * rinv;
;                   o4.x = pack2(t0 * t0, t1 * t1); o4.y = pack2(t2 * t2, t3 * t3); }
;                 { const float t0 = fmaxf(v1[0], 0.f) * rinv, t1 = fmaxf(v1[1], 0.f) * rinv, t2 = fmaxf(v1[2], 0.f) * rinv, t3 = fmaxf(v1[3], 0.f) * rinv;
;                   o4.z = pack2(t0 * t0, t1 * t1); o4.w = pack2(t2 * t2, t3 * t3); }
;                 *(u32x4*)((u16*)big + (size_t)token * 4096 + u.pn * 256 + bj * 128 + wc * 32 + 8 * fq) = o4;
;               }
;             }
;           }
;         if (EPI == EPI_RESID) {
;           ssq += shx(ssq, 16, t_ & 63);
;           ssq += shx(ssq, 32, t_ & 63);
;           if (fq == 0) ss_out[(size_t)token * 16 + u.pn * 4 + wc] = ssq;
.LBB0_1675:
	v_pk_add_f32 v[84:85], v[84:85], v[88:89]
	v_mul_f32_e32 v102, v111, v111
	v_pk_add_f32 v[86:87], v[86:87], v[90:91]
	v_pk_add_f32 v[90:91], v[80:81], v[92:93]
	v_mul_f32_e32 v80, v85, v85
	v_fmac_f32_e32 v102, v110, v110
	v_fmac_f32_e32 v80, v84, v84
	v_fmac_f32_e32 v102, v98, v98
	v_fmac_f32_e32 v80, v86, v86
	v_fmac_f32_e32 v102, v99, v99
	v_fmac_f32_e32 v80, v87, v87
	v_fmac_f32_e32 v102, v100, v100
	v_fmac_f32_e32 v80, v90, v90
	v_fmac_f32_e32 v102, v101, v101
	v_pk_add_f32 v[88:89], v[82:83], v[94:95]
	v_fmac_f32_e32 v80, v91, v91
	v_fmac_f32_e32 v102, v96, v96
	v_fmac_f32_e32 v80, v88, v88
	v_fmac_f32_e32 v102, v97, v97
	v_fmac_f32_e32 v80, v89, v89
	v_add_f32_e32 v80, v102, v80
	v_mov_b32_e32 v247, v80
	v_cvt_pk_bf16_f32 v82, v84, v85
	v_cvt_pk_bf16_f32 v83, v86, v87
	v_cvt_pk_bf16_f32 v84, v90, v91
	v_cvt_pk_bf16_f32 v85, v88, v89
	global_store_dwordx4 v[106:107], v[82:85], off offset:256
	v_or_b32_e32 v88, 48, v150
	v_ashrrev_i32_e32 v89, 31, v88
	s_waitcnt lgkmcnt(0)
	v_lshlrev_b64 v[80:81], 12, v[88:89]
	v_lshl_add_u64 v[80:81], s[6:7], 0, v[80:81]
	s_and_b64 vcc, exec, s[2:3]
	v_lshl_add_u64 v[92:93], v[148:149], 2, v[80:81]
	s_cbranch_vccnz .LBB0_1680
	v_mov_b64_e32 v[84:85], v[228:229]
	v_mov_b64_e32 v[86:87], v[230:231]
	v_mov_b64_e32 v[80:81], v[224:225]
	v_mov_b64_e32 v[82:83], v[226:227]
	s_mov_b64 s[34:35], 0
	s_branch .LBB0_1681

; DI float bf2f(unsigned v) { return __uint_as_float(v << 16); }
;   DI void operator()(const f32x4 (&acc)[2][2][4][2], const pg8::Unit& u, int wr, int wc, int fr_, int fq_) const {
;     ...
;             } else if (EPI == EPI_RESID) {
;               if (n == 0) {
;                 const int f8 = u.pn * 256 + bj * 128 + wc * 32 + 8 * fq;
;                 const f32x4 v1 = acc[ai][bj][m][1];
;                 f32x4 r0, r1;
;                 if (rsrc) {
;                   r0 = *(const f32x4*)(rsrc + (size_t)token * 1024 + f8); r1 = *(const f32x4*)(rsrc + (size_t)token * 1024 + f8 + 4);
;                 } else {
;                   const u32x4 xu = *(const u32x4*)(xr + (size_t)token * 1024 + f8);
;                   r0 = (f32x4){bf2f(xu.x & 0xffffu), bf2f(xu.x >> 16), bf2f(xu.y & 0xffffu), bf2f(xu.y >> 16)};
;                   r1 = (f32x4){bf2f(xu.z & 0xffffu), bf2f(xu.z >> 16), bf2f(xu.w & 0xffffu), bf2f(xu.w >> 16)};
;                 }
;                 r0 += v; r1 += v1;
;                 st_bf8(xr + (size_t)token * 1024 + f8, r0, r1, 1.f);
;                 ssq += r0[0] * r0[0] + r0[1] * r0[1] + r0[2] * r0[2] + r0[3] * r0[3] + r1[0] * r1[0] + r1[1] * r1[1] + r1[2] * r1[2] + r1[3] * r1[3];
;               }
;             } else {
;               if (n == 0) {
;                 const f32x4 v1 = acc[ai][bj][m][1];
;                 u32x4 o4;
;                 { const float t0 = fmaxf(v[0], 0.f) * rinv, t1 = fmaxf(v[1], 0.f) * rinv, t2 = fmaxf(v[2], 0.f) * rinv, t3 = fmaxf(v[3], 0.f) * rinv;
;                   o4.x = pack2(t0 * t0, t1 * t1); o4.y = pack2(t2 * t2, t3 * t3); }
;                 { const float t0 = fmaxf(v1[0], 0.f) * rinv, t1 = fmaxf(v1[1], 0.f) * rinv, t2 = fmaxf(v1[2], 0.f) * rinv, t3 = fmaxf(v1[3], 0.f) * rinv;
;                   o4.z = pack2(t0 * t0, t1 * t1); o4.w = pack2(t2 * t2, t3 * t3); }
;                 *(u32x4*)((u16*)big + (size_t)token * 4096 + u.pn * 256 + bj * 128 + wc * 32 + 8 * fq) = o4;
;               }
;             }
;           }
;         if (EPI == EPI_RESID) {
;           ssq += shx(ssq, 16, t_ & 63);
;           ssq += shx(ssq, 32, t_ & 63);
;           if (fq == 0) ss_out[(size_t)token * 16 + u.pn * 4 + wc] = ssq;
.LBB0_1686:
	v_pk_add_f32 v[68:69], v[68:69], v[72:73]
	v_mul_f32_e32 v86, v95, v95
	v_pk_add_f32 v[70:71], v[70:71], v[74:75]
	v_pk_add_f32 v[74:75], v[64:65], v[76:77]
	v_mul_f32_e32 v64, v69, v69
	v_fmac_f32_e32 v86, v94, v94
	v_fmac_f32_e32 v64, v68, v68
	v_fmac_f32_e32 v86, v82, v82
	v_fmac_f32_e32 v64, v70, v70
	v_fmac_f32_e32 v86, v83, v83
	v_fmac_f32_e32 v64, v71, v71
	v_fmac_f32_e32 v86, v84, v84
	v_fmac_f32_e32 v64, v74, v74
	v_fmac_f32_e32 v86, v85, v85
	v_pk_add_f32 v[72:73], v[66:67], v[78:79]
	v_fmac_f32_e32 v64, v75, v75
	v_fmac_f32_e32 v86, v80, v80
	v_fmac_f32_e32 v64, v72, v72
	v_fmac_f32_e32 v86, v81, v81
	v_fmac_f32_e32 v64, v73, v73
	v_add_f32_e32 v64, v86, v64
	v_mov_b32_e32 v248, v64
	v_cvt_pk_bf16_f32 v66, v68, v69
	v_cvt_pk_bf16_f32 v67, v70, v71
	v_cvt_pk_bf16_f32 v68, v74, v75
	v_cvt_pk_bf16_f32 v69, v72, v73
	global_store_dwordx4 v[90:91], v[66:69], off offset:256
	v_add_u32_e32 v72, 0x80, v150
	v_ashrrev_i32_e32 v73, 31, v72
	s_waitcnt lgkmcnt(0)
	v_lshlrev_b64 v[64:65], 12, v[72:73]
	v_lshl_add_u64 v[64:65], s[6:7], 0, v[64:65]
	s_and_b64 vcc, exec, s[2:3]
	v_lshl_add_u64 v[76:77], v[148:149], 2, v[64:65]
	s_cbranch_vccnz .LBB0_1691
	v_add_u32_e32 v251, 0x50000, v251
	global_load_dwordx4 v[162:165], v251, s[6:7]
	global_load_dwordx4 v[166:169], v251, s[6:7] offset:16
	global_load_dwordx4 v[170:173], v251, s[6:7] offset:512
	global_load_dwordx4 v[174:177], v251, s[6:7] offset:528
	v_add_u32_e32 v251, 0x10000, v251
	global_load_dwordx4 v[178:181], v251, s[6:7]
	global_load_dwordx4 v[196:199], v251, s[6:7] offset:16
	global_load_dwordx4 v[200:203], v251, s[6:7] offset:512
	global_load_dwordx4 v[204:207], v251, s[6:7] offset:528
	v_add_u32_e32 v251, 0x10000, v251
	global_load_dwordx4 v[208:211], v251, s[6:7]
	global_load_dwordx4 v[212:215], v251, s[6:7] offset:16
	global_load_dwordx4 v[216:219], v251, s[6:7] offset:512
	global_load_dwordx4 v[220:223], v251, s[6:7] offset:528
	v_add_u32_e32 v251, 0x10000, v251
	global_load_dwordx4 v[224:227], v251, s[6:7]
	global_load_dwordx4 v[228:231], v251, s[6:7] offset:16
	global_load_dwordx4 v[232:235], v251, s[6:7] offset:512
	global_load_dwordx4 v[242:245], v251, s[6:7] offset:528
	s_waitcnt vmcnt(0)
	v_mov_b64_e32 v[68:69], v[166:167]
	v_mov_b64_e32 v[70:71], v[168:169]
	v_mov_b64_e32 v[64:65], v[162:163]
	v_mov_b64_e32 v[66:67], v[164:165]
	s_mov_b64 s[34:35], 0
	s_branch .LBB0_1692

; DI float bf2f(unsigned v) { return __uint_as_float(v << 16); }
;   DI void operator()(const f32x4 (&acc)[2][2][4][2], const pg8::Unit& u, int wr, int wc, int fr_, int fq_) const {
;     ...
;             } else if (EPI == EPI_RESID) {
;               if (n == 0) {
;                 const int f8 = u.pn * 256 + bj * 128 + wc * 32 + 8 * fq;
;                 const f32x4 v1 = acc[ai][bj][m][1];
;                 f32x4 r0, r1;
;                 if (rsrc) {
;                   r0 = *(const f32x4*)(rsrc + (size_t)token * 1024 + f8); r1 = *(const f32x4*)(rsrc + (size_t)token * 1024 + f8 + 4);
;                 } else {
;                   const u32x4 xu = *(const u32x4*)(xr + (size_t)token * 1024 + f8);
;                   r0 = (f32x4){bf2f(xu.x & 0xffffu), bf2f(xu.x >> 16), bf2f(xu.y & 0xffffu), bf2f(xu.y >> 16)};
;                   r1 = (f32x4){bf2f(xu.z & 0xffffu), bf2f(xu.z >> 16), bf2f(xu.w & 0xffffu), bf2f(xu.w >> 16)};
;                 }
;                 r0 += v; r1 += v1;
;                 st_bf8(xr + (size_t)token * 1024 + f8, r0, r1, 1.f);
;                 ssq += r0[0] * r0[0] + r0[1] * r0[1] + r0[2] * r0[2] + r0[3] * r0[3] + r1[0] * r1[0] + r1[1] * r1[1] + r1[2] * r1[2] + r1[3] * r1[3];
;               }
;             } else {
;               if (n == 0) {
;                 const f32x4 v1 = acc[ai][bj][m][1];
;                 u32x4 o4;
;                 { const float t0 = fmaxf(v[0], 0.f) * rinv, t1 = fmaxf(v[1], 0.f) * rinv, t2 = fmaxf(v[2], 0.f) * rinv, t3 = fmaxf(v[3], 0.f) * rinv;
;                   o4.x = pack2(t0 * t0, t1 * t1); o4.y = pack2(t2 * t2, t3 * t3); }
;                 { const float t0 = fmaxf(v1[0], 0.f) * rinv, t1 = fmaxf(v1[1], 0.f) * rinv, t2 = fmaxf(v1[2], 0.f) * rinv, t3 = fmaxf(v1[3], 0.f) * rinv;
;                   o4.z = pack2(t0 * t0, t1 * t1); o4.w = pack2(t2 * t2, t3 * t3); }
;                 *(u32x4*)((u16*)big + (size_t)token * 4096 + u.pn * 256 + bj * 128 + wc * 32 + 8 * fq) = o4;
;               }
;             }
;           }
;         if (EPI == EPI_RESID) {
;           ssq += shx(ssq, 16, t_ & 63);
;           ssq += shx(ssq, 32, t_ & 63);
;           if (fq == 0) ss_out[(size_t)token * 16 + u.pn * 4 + wc] = ssq;
.LBB0_1697:
	v_pk_add_f32 v[52:53], v[52:53], v[56:57]
	v_mul_f32_e32 v70, v79, v79
	v_pk_add_f32 v[54:55], v[54:55], v[58:59]
	v_pk_add_f32 v[58:59], v[48:49], v[60:61]
	v_mul_f32_e32 v48, v53, v53
	v_fmac_f32_e32 v70, v78, v78
	v_fmac_f32_e32 v48, v52, v52
	v_fmac_f32_e32 v70, v66, v66
	v_fmac_f32_e32 v48, v54, v54
	v_fmac_f32_e32 v70, v67, v67
	v_fmac_f32_e32 v48, v55, v55
	v_fmac_f32_e32 v70, v68, v68
	v_fmac_f32_e32 v48, v58, v58
	v_fmac_f32_e32 v70, v69, v69
	v_pk_add_f32 v[56:57], v[50:51], v[62:63]
	v_fmac_f32_e32 v48, v59, v59
	v_fmac_f32_e32 v70, v64, v64
	v_fmac_f32_e32 v48, v56, v56
	v_fmac_f32_e32 v70, v65, v65
	v_fmac_f32_e32 v48, v57, v57
	v_add_f32_e32 v48, v70, v48
	v_mov_b32_e32 v249, v48
	v_cvt_pk_bf16_f32 v50, v52, v53
	v_cvt_pk_bf16_f32 v51, v54, v55
	v_cvt_pk_bf16_f32 v52, v58, v59
	v_cvt_pk_bf16_f32 v53, v56, v57
	global_store_dwordx4 v[74:75], v[50:53], off offset:256
	v_add_u32_e32 v56, 0x90, v150
	v_ashrrev_i32_e32 v57, 31, v56
	s_waitcnt lgkmcnt(0)
	v_lshlrev_b64 v[48:49], 12, v[56:57]
	v_lshl_add_u64 v[48:49], s[6:7], 0, v[48:49]
	s_and_b64 vcc, exec, s[2:3]
	v_lshl_add_u64 v[60:61], v[148:149], 2, v[48:49]
	s_cbranch_vccnz .LBB0_1702
	v_mov_b64_e32 v[52:53], v[196:197]
	v_mov_b64_e32 v[54:55], v[198:199]
	v_mov_b64_e32 v[48:49], v[178:179]
	v_mov_b64_e32 v[50:51], v[180:181]
	s_mov_b64 s[34:35], 0
	s_branch .LBB0_1703

; DI float bf2f(unsigned v) { return __uint_as_float(v << 16); }
;   DI void operator()(const f32x4 (&acc)[2][2][4][2], const pg8::Unit& u, int wr, int wc, int fr_, int fq_) const {
;     ...
;             } else if (EPI == EPI_RESID) {
;               if (n == 0) {
;                 const int f8 = u.pn * 256 + bj * 128 + wc * 32 + 8 * fq;
;                 const f32x4 v1 = acc[ai][bj][m][1];
;                 f32x4 r0, r1;
;                 if (rsrc) {
;                   r0 = *(const f32x4*)(rsrc + (size_t)token * 1024 + f8); r1 = *(const f32x4*)(rsrc + (size_t)token * 1024 + f8 + 4);
;                 } else {
;                   const u32x4 xu = *(const u32x4*)(xr + (size_t)token * 1024 + f8);
;                   r0 = (f32x4){bf2f(xu.x & 0xffffu), bf2f(xu.x >> 16), bf2f(xu.y & 0xffffu), bf2f(xu.y >> 16)};
;                   r1 = (f32x4){bf2f(xu.z & 0xffffu), bf2f(xu.z >> 16), bf2f(xu.w & 0xffffu), bf2f(xu.w >> 16)};
;                 }
;                 r0 += v; r1 += v1;
;                 st_bf8(xr + (size_t)token * 1024 + f8, r0, r1, 1.f);
;                 ssq += r0[0] * r0[0] + r0[1] * r0[1] + r0[2] * r0[2] + r0[3] * r0[3] + r1[0] * r1[0] + r1[1] * r1[1] + r1[2] * r1[2] + r1[3] * r1[3];
;               }
;             } else {
;               if (n == 0) {
;                 const f32x4 v1 = acc[ai][bj][m][1];
;                 u32x4 o4;
;                 { const float t0 = fmaxf(v[0], 0.f) * rinv, t1 = fmaxf(v[1], 0.f) * rinv, t2 = fmaxf(v[2], 0.f) * rinv, t3 = fmaxf(v[3], 0.f) * rinv;
;                   o4.x = pack2(t0 * t0, t1 * t1); o4.y = pack2(t2 * t2, t3 * t3); }
;                 { const float t0 = fmaxf(v1[0], 0.f) * rinv, t1 = fmaxf(v1[1], 0.f) * rinv, t2 = fmaxf(v1[2], 0.f) * rinv, t3 = fmaxf(v1[3], 0.f) * rinv;
;                   o4.z = pack2(t0 * t0, t1 * t1); o4.w = pack2(t2 * t2, t3 * t3); }
;                 *(u32x4*)((u16*)big + (size_t)token * 4096 + u.pn * 256 + bj * 128 + wc * 32 + 8 * fq) = o4;
;               }
;             }
;           }
;         if (EPI == EPI_RESID) {
;           ssq += shx(ssq, 16, t_ & 63);
;           ssq += shx(ssq, 32, t_ & 63);
;           if (fq == 0) ss_out[(size_t)token * 16 + u.pn * 4 + wc] = ssq;
.LBB0_1708:
	v_pk_add_f32 v[36:37], v[36:37], v[40:41]
	v_mul_f32_e32 v54, v63, v63
	v_pk_add_f32 v[38:39], v[38:39], v[42:43]
	v_pk_add_f32 v[42:43], v[32:33], v[44:45]
	v_mul_f32_e32 v32, v37, v37
	v_fmac_f32_e32 v54, v62, v62
	v_fmac_f32_e32 v32, v36, v36
	v_fmac_f32_e32 v54, v50, v50
	v_fmac_f32_e32 v32, v38, v38
	v_fmac_f32_e32 v54, v51, v51
	v_fmac_f32_e32 v32, v39, v39
	v_fmac_f32_e32 v54, v52, v52
	v_fmac_f32_e32 v32, v42, v42
	v_fmac_f32_e32 v54, v53, v53
	v_pk_add_f32 v[40:41], v[34:35], v[46:47]
	v_fmac_f32_e32 v32, v43, v43
	v_fmac_f32_e32 v54, v48, v48
	v_fmac_f32_e32 v32, v40, v40
	v_fmac_f32_e32 v54, v49, v49
	v_fmac_f32_e32 v32, v41, v41
	v_add_f32_e32 v32, v54, v32
	v_mov_b32_e32 v252, v32
	v_cvt_pk_bf16_f32 v34, v36, v37
	v_cvt_pk_bf16_f32 v35, v38, v39
	v_cvt_pk_bf16_f32 v36, v42, v43
	v_cvt_pk_bf16_f32 v37, v40, v41
	global_store_dwordx4 v[58:59], v[34:37], off offset:256
	v_add_u32_e32 v40, 0xa0, v150
	v_ashrrev_i32_e32 v41, 31, v40
	s_waitcnt lgkmcnt(0)
	v_lshlrev_b64 v[32:33], 12, v[40:41]
	v_lshl_add_u64 v[32:33], s[6:7], 0, v[32:33]
	s_and_b64 vcc, exec, s[2:3]
	v_lshl_add_u64 v[44:45], v[148:149], 2, v[32:33]
	s_cbranch_vccnz .LBB0_1713
	v_mov_b64_e32 v[36:37], v[212:213]
	v_mov_b64_e32 v[38:39], v[214:215]
	v_mov_b64_e32 v[32:33], v[208:209]
	v_mov_b64_e32 v[34:35], v[210:211]
	s_mov_b64 s[34:35], 0
	s_branch .LBB0_1714

; DI float bf2f(unsigned v) { return __uint_as_float(v << 16); }
;   DI void operator()(const f32x4 (&acc)[2][2][4][2], const pg8::Unit& u, int wr, int wc, int fr_, int fq_) const {
;     ...
;             } else if (EPI == EPI_RESID) {
;               if (n == 0) {
;                 const int f8 = u.pn * 256 + bj * 128 + wc * 32 + 8 * fq;
;                 const f32x4 v1 = acc[ai][bj][m][1];
;                 f32x4 r0, r1;
;                 if (rsrc) {
;                   r0 = *(const f32x4*)(rsrc + (size_t)token * 1024 + f8); r1 = *(const f32x4*)(rsrc + (size_t)token * 1024 + f8 + 4);
;                 } else {
;                   const u32x4 xu = *(const u32x4*)(xr + (size_t)token * 1024 + f8);
;                   r0 = (f32x4){bf2f(xu.x & 0xffffu), bf2f(xu.x >> 16), bf2f(xu.y & 0xffffu), bf2f(xu.y >> 16)};
;                   r1 = (f32x4){bf2f(xu.z & 0xffffu), bf2f(xu.z >> 16), bf2f(xu.w & 0xffffu), bf2f(xu.w >> 16)};
;                 }
;                 r0 += v; r1 += v1;
;                 st_bf8(xr + (size_t)token * 1024 + f8, r0, r1, 1.f);
;                 ssq += r0[0] * r0[0] + r0[1] * r0[1] + r0[2] * r0[2] + r0[3] * r0[3] + r1[0] * r1[0] + r1[1] * r1[1] + r1[2] * r1[2] + r1[3] * r1[3];
;               }
;             } else {
;               if (n == 0) {
;                 const f32x4 v1 = acc[ai][bj][m][1];
;                 u32x4 o4;
;                 { const float t0 = fmaxf(v[0], 0.f) * rinv, t1 = fmaxf(v[1], 0.f) * rinv, t2 = fmaxf(v[2], 0.f) * rinv, t3 = fmaxf(v[3], 0.f) * rinv;
;                   o4.x = pack2(t0 * t0, t1 * t1); o4.y = pack2(t2 * t2, t3 * t3); }
;                 { const float t0 = fmaxf(v1[0], 0.f) * rinv, t1 = fmaxf(v1[1], 0.f) * rinv, t2 = fmaxf(v1[2], 0.f) * rinv, t3 = fmaxf(v1[3], 0.f) * rinv;
;                   o4.z = pack2(t0 * t0, t1 * t1); o4.w = pack2(t2 * t2, t3 * t3); }
;                 *(u32x4*)((u16*)big + (size_t)token * 4096 + u.pn * 256 + bj * 128 + wc * 32 + 8 * fq) = o4;
;               }
;             }
;           }
;         if (EPI == EPI_RESID) {
;           ssq += shx(ssq, 16, t_ & 63);
;           ssq += shx(ssq, 32, t_ & 63);
;           if (fq == 0) ss_out[(size_t)token * 16 + u.pn * 4 + wc] = ssq;
.LBB0_1719:
	v_pk_add_f32 v[20:21], v[20:21], v[24:25]
	v_mul_f32_e32 v38, v47, v47
	v_pk_add_f32 v[22:23], v[22:23], v[26:27]
	v_pk_add_f32 v[26:27], v[16:17], v[28:29]
	v_mul_f32_e32 v16, v21, v21
	v_fmac_f32_e32 v38, v46, v46
	v_fmac_f32_e32 v16, v20, v20
	v_fmac_f32_e32 v38, v34, v34
	v_fmac_f32_e32 v16, v22, v22
	v_fmac_f32_e32 v38, v35, v35
	v_fmac_f32_e32 v16, v23, v23
	v_fmac_f32_e32 v38, v36, v36
	v_fmac_f32_e32 v16, v26, v26
	v_fmac_f32_e32 v38, v37, v37
	v_pk_add_f32 v[24:25], v[18:19], v[30:31]
	v_fmac_f32_e32 v16, v27, v27
	v_fmac_f32_e32 v38, v32, v32
	v_fmac_f32_e32 v16, v24, v24
	v_fmac_f32_e32 v38, v33, v33
	v_fmac_f32_e32 v16, v25, v25
	v_add_f32_e32 v16, v38, v16
	v_mov_b32_e32 v253, v16
	v_cvt_pk_bf16_f32 v18, v20, v21
	v_cvt_pk_bf16_f32 v19, v22, v23
	v_cvt_pk_bf16_f32 v20, v26, v27
	v_cvt_pk_bf16_f32 v21, v24, v25
	global_store_dwordx4 v[42:43], v[18:21], off offset:256
	v_add_u32_e32 v24, 0xb0, v150
	v_ashrrev_i32_e32 v25, 31, v24
	s_waitcnt lgkmcnt(0)
	v_lshlrev_b64 v[16:17], 12, v[24:25]
	v_lshl_add_u64 v[16:17], s[6:7], 0, v[16:17]
	s_and_b64 vcc, exec, s[2:3]
	v_lshl_add_u64 v[28:29], v[148:149], 2, v[16:17]
	s_cbranch_vccnz .LBB0_1724
	v_mov_b64_e32 v[20:21], v[228:229]
	v_mov_b64_e32 v[22:23], v[230:231]
	v_mov_b64_e32 v[16:17], v[224:225]
	v_mov_b64_e32 v[18:19], v[226:227]
	s_mov_b64 s[34:35], 0
	s_branch .LBB0_1725

;   DI void operator()(const f32x4 (&acc)[2][2][4][2], const pg8::Unit& u, int wr, int wc, int fr_, int fq_) const {
;     ...
;                 r0 += v; r1 += v1;
;                 st_bf8(xr + (size_t)token * 1024 + f8, r0, r1, 1.f);
;                 ssq += r0[0] * r0[0] + r0[1] * r0[1] + r0[2] * r0[2] + r0[3] * r0[3] + r1[0] * r1[0] + r1[1] * r1[1] + r1[2] * r1[2] + r1[3] * r1[3];
;               }
;             } else {
;               if (n == 0) {
;                 const f32x4 v1 = acc[ai][bj][m][1];
;                 u32x4 o4;
;                 { const float t0 = fmaxf(v[0], 0.f) * rinv, t1 = fmaxf(v[1], 0.f) * rinv, t2 = fmaxf(v[2], 0.f) * rinv, t3 = fmaxf(v[3], 0.f) * rinv;
;                   o4.x = pack2(t0 * t0, t1 * t1); o4.y = pack2(t2 * t2, t3 * t3); }
;                 { const float t0 = fmaxf(v1[0], 0.f) * rinv, t1 = fmaxf(v1[1], 0.f) * rinv, t2 = fmaxf(v1[2], 0.f) * rinv, t3 = fmaxf(v1[3], 0.f) * rinv;
;                   o4.z = pack2(t0 * t0, t1 * t1); o4.w = pack2(t2 * t2, t3 * t3); }
;                 *(u32x4*)((u16*)big + (size_t)token * 4096 + u.pn * 256 + bj * 128 + wc * 32 + 8 * fq) = o4;
;               }
;             }
;           }
;         if (EPI == EPI_RESID) {
;           ssq += shx(ssq, 16, t_ & 63);
;           ssq += shx(ssq, 32, t_ & 63);
;           if (fq == 0) ss_out[(size_t)token * 16 + u.pn * 4 + wc] = ssq;
.LBB0_1730:
	v_pk_add_f32 v[4:5], v[4:5], v[8:9]
	v_mul_f32_e32 v22, v31, v31
	v_pk_add_f32 v[6:7], v[6:7], v[10:11]
	v_pk_add_f32 v[10:11], v[0:1], v[12:13]
	v_mul_f32_e32 v0, v5, v5
	v_fmac_f32_e32 v22, v30, v30
	v_fmac_f32_e32 v0, v4, v4
	v_fmac_f32_e32 v22, v18, v18
	v_fmac_f32_e32 v0, v6, v6
	v_fmac_f32_e32 v22, v19, v19
	v_fmac_f32_e32 v0, v7, v7
	v_fmac_f32_e32 v22, v20, v20
	v_fmac_f32_e32 v0, v10, v10
	v_fmac_f32_e32 v22, v21, v21
	v_pk_add_f32 v[8:9], v[2:3], v[14:15]
	v_fmac_f32_e32 v0, v11, v11
	v_fmac_f32_e32 v22, v16, v16
	v_fmac_f32_e32 v0, v8, v8
	v_fmac_f32_e32 v22, v17, v17
	v_fmac_f32_e32 v0, v9, v9
	v_add_f32_e32 v0, v22, v0
	v_mov_b32_e32 v254, v0
	v_cvt_pk_bf16_f32 v2, v4, v5
	v_cvt_pk_bf16_f32 v3, v6, v7
	v_cvt_pk_bf16_f32 v4, v10, v11
	v_cvt_pk_bf16_f32 v5, v8, v9
	global_store_dwordx4 v[26:27], v[2:5], off offset:256
	ds_bpermute_b32 v162, v129, v236
	ds_bpermute_b32 v163, v129, v246
	ds_bpermute_b32 v164, v129, v247
	ds_bpermute_b32 v165, v129, v248
	ds_bpermute_b32 v166, v129, v249
	ds_bpermute_b32 v167, v129, v252
	ds_bpermute_b32 v168, v129, v253
	ds_bpermute_b32 v169, v129, v254
	s_waitcnt lgkmcnt(0)
	v_add_f32_e32 v236, v236, v162
	v_add_f32_e32 v246, v246, v163
	v_add_f32_e32 v247, v247, v164
	v_add_f32_e32 v248, v248, v165
	v_add_f32_e32 v249, v249, v166
	v_add_f32_e32 v252, v252, v167
	v_add_f32_e32 v253, v253, v168
	v_add_f32_e32 v254, v254, v169
	ds_bpermute_b32 v162, v128, v236
	ds_bpermute_b32 v163, v128, v246
	ds_bpermute_b32 v164, v128, v247
	ds_bpermute_b32 v165, v128, v248
	ds_bpermute_b32 v166, v128, v249
	ds_bpermute_b32 v167, v128, v252
	ds_bpermute_b32 v168, v128, v253
	ds_bpermute_b32 v169, v128, v254
	s_and_saveexec_b64 s[2:3], s[4:5]
	s_cbranch_execz .LBB0_1636
	s_waitcnt lgkmcnt(0)
	v_add_f32_e32 v236, v236, v162
	v_add_f32_e32 v246, v246, v163
	v_add_f32_e32 v247, v247, v164
	v_add_f32_e32 v248, v248, v165
	v_add_f32_e32 v249, v249, v166
	v_add_f32_e32 v252, v252, v167
	v_add_f32_e32 v253, v253, v168
	v_add_f32_e32 v254, v254, v169
	v_lshlrev_b64 v[170:171], 6, v[150:151]
	v_lshl_add_u64 v[170:171], s[10:11], 0, v[170:171]
	v_lshl_add_u64 v[170:171], s[28:29], 2, v[170:171]
	s_lshl_b32 s24, s46, 2
	v_lshl_add_u64 v[170:171], v[170:171], 0, s[24:25]
	global_store_dword v[170:171], v236, off
	global_store_dword v[170:171], v246, off offset:1024
	global_store_dword v[170:171], v247, off offset:2048
	global_store_dword v[170:171], v248, off offset:3072
	s_mov_b64 vcc, 0x2000
	v_lshl_add_u64 v[170:171], v[170:171], 0, vcc
	global_store_dword v[170:171], v249, off
	global_store_dword v[170:171], v252, off offset:1024
	global_store_dword v[170:171], v253, off offset:2048
	global_store_dword v[170:171], v254, off offset:3072
	s_branch .LBB0_1636

; #define PG8_STAGE(bufoff, gbase, voff) do { _Pragma("unroll") for (int _i = 0; _i < 2; ++_i) \
;     __builtin_amdgcn_global_load_lds((const unsigned*)((const char*)(gbase) + (voff)[_i]), (LAS unsigned*)(lds + (bufoff) + ldsw + _i * 8192), 16, 0, 0); } while (0)
; #define PG8_LDA(dst, b, h) do { _Pragma("unroll") for (int m = 0; m < 4; ++m) _Pragma("unroll") for (int k = 0; k < 2; ++k) dst[m][k] = *(const LAS bf16x8*)(lds + PG8_SA(b, h) + aoff + m * 2048 + k * 1024); } while (0)
; #define PG8_LDB(dst, b, h) do { _Pragma("unroll") for (int n = 0; n < 2; ++n) _Pragma("unroll") for (int k = 0; k < 2; ++k) dst[n][k] = *(const LAS bf16x8*)(lds + PG8_SB(b, h) + boff + n * 2048 + k * 1024); } while (0)
; #define PG8_MMA(ai, bj, At, Bt) do { __builtin_amdgcn_s_setprio(1); _Pragma("unroll") for (int m = 0; m < 4; ++m) _Pragma("unroll") for (int n = 0; n < 2; ++n) _Pragma("unroll") for (int k = 0; k < 2; ++k) \
;     acc[ai][bj][m][n] = __builtin_amdgcn_mfma_f32_16x16x32_bf16(Bt[n][k], At[m][k], acc[ai][bj][m][n], 0, 0, 0); __builtin_amdgcn_s_setprio(0); } while (0)
; #define PG8_WAIT_V(n) asm volatile("s_waitcnt vmcnt(" #n ")" ::: "memory")
; #define PG8_WAIT_L(n) asm volatile("s_waitcnt lgkmcnt(" #n ")" ::: "memory")
; #define PG8_BAR __builtin_amdgcn_s_barrier()
; #define PG8_SCHED __builtin_amdgcn_sched_barrier(0)
; template <class Epi, class Sched>
; DI void gemm_phase(LAS unsigned char* lds, const Gemm g, const Sched& S, const Epi& E) {
;     ...
;     for (int t = 0; t < nt; t += 2) {
;       const bool last = (t == nt - 2);
;       const char* a1 = cA + (size_t)(t + 1) * kstep;
;       const char* a2 = last ? nA : cA + (size_t)(t + 2) * kstep; const char* b2 = last ? nB : cB + (size_t)(t + 2) * kstep;
;       const char* a3 = a2 + kstep; const char* b3 = b2 + kstep;
;       PG8_LDB(B0, 0, 0); PG8_SCHED; PG8_LDA(At, 0, 0); PG8_STAGE(PG8_SA(1, 1), a1 + hstep, voffA);
;       PG8_WAIT_L(8); PG8_BAR; PG8_WAIT_L(0); PG8_MMA(0, 0, At, B0); PG8_BAR; PG8_SCHED;
;       PG8_LDB(B1, 0, 1); PG8_STAGE(PG8_SB(0, 0), b2, voffB);
;       PG8_BAR; PG8_WAIT_L(0); PG8_MMA(0, 1, At, B1); PG8_BAR;
;       PG8_LDA(At, 0, 1); PG8_STAGE(PG8_SA(0, 0), a2, voffA);
;       PG8_BAR; PG8_WAIT_L(0); PG8_MMA(1, 0, At, B0); PG8_BAR; PG8_SCHED;
;       PG8_STAGE(PG8_SB(0, 1), b2 + hstep, voffB);
;       PG8_WAIT_V(6); PG8_BAR; PG8_MMA(1, 1, At, B1); PG8_BAR;
.LBB0_1905:
	s_add_u32 s22, s20, 0xfff00080
	s_addc_u32 s23, s21, -1
	s_add_i32 s51, 0, 0x10000
	ds_read_b128 v[138:141], v224
	ds_read_b128 v[148:151], v224 offset:1024
	ds_read_b128 v[152:155], v224 offset:2048
	ds_read_b128 v[156:159], v224 offset:3072
	s_cmp_eq_u32 s50, 60
	s_cselect_b32 s29, s11, s23
	s_cselect_b32 s28, s17, s22
	s_cselect_b32 s23, s7, s49
	s_cselect_b32 s22, s19, s24
	s_add_i32 m0, s39, 0xc000
	ds_read_b128 v[160:163], v147
	ds_read_b128 v[164:167], v147 offset:1024
	ds_read_b128 v[168:171], v147 offset:2048
	ds_read_b128 v[172:175], v147 offset:3072
	ds_read_b128 v[176:179], v147 offset:4096
	ds_read_b128 v[196:199], v147 offset:5120
	ds_read_b128 v[200:203], v147 offset:6144
	ds_read_b128 v[204:207], v147 offset:7168
	global_load_lds_dwordx4 v134, s[20:21]
	s_add_i32 m0, s39, 0xe000
	s_nop 0
	global_load_lds_dwordx4 v136, s[20:21]
	s_waitcnt lgkmcnt(8)
	s_barrier
	s_waitcnt lgkmcnt(0)
	v_mfma_f32_16x16x32_bf16 v[124:127], v[138:141], v[160:163], v[124:127]
	v_mfma_f32_16x16x32_bf16 v[120:123], v[152:155], v[160:163], v[120:123]
	v_mfma_f32_16x16x32_bf16 v[108:111], v[138:141], v[168:171], v[108:111]
	v_mfma_f32_16x16x32_bf16 v[104:107], v[152:155], v[168:171], v[104:107]
	v_mfma_f32_16x16x32_bf16 v[92:95], v[138:141], v[176:179], v[92:95]
	v_mfma_f32_16x16x32_bf16 v[88:91], v[152:155], v[176:179], v[88:91]
	v_mfma_f32_16x16x32_bf16 v[76:79], v[138:141], v[200:203], v[76:79]
	v_mfma_f32_16x16x32_bf16 v[72:75], v[152:155], v[200:203], v[72:75]
	v_mfma_f32_16x16x32_bf16 v[124:127], v[148:151], v[164:167], v[124:127]
	v_mfma_f32_16x16x32_bf16 v[120:123], v[156:159], v[164:167], v[120:123]
	v_mfma_f32_16x16x32_bf16 v[108:111], v[148:151], v[172:175], v[108:111]
	v_mfma_f32_16x16x32_bf16 v[104:107], v[156:159], v[172:175], v[104:107]
	v_mfma_f32_16x16x32_bf16 v[92:95], v[148:151], v[196:199], v[92:95]
	v_mfma_f32_16x16x32_bf16 v[88:91], v[156:159], v[196:199], v[88:91]
	v_mfma_f32_16x16x32_bf16 v[76:79], v[148:151], v[204:207], v[76:79]
	v_mfma_f32_16x16x32_bf16 v[72:75], v[156:159], v[204:207], v[72:75]
	s_barrier
	s_add_i32 s54, 0, 0x14000
	s_add_i32 s51, s51, s38
	ds_read_b128 v[208:211], v225
	ds_read_b128 v[212:215], v225 offset:1024
	ds_read_b128 v[216:219], v225 offset:2048
	ds_read_b128 v[220:223], v225 offset:3072
	s_add_u32 vcc_lo, s22, s0
	s_addc_u32 vcc_hi, s23, s1
	s_mov_b32 m0, s51
	s_nop 0
	global_load_lds_dwordx4 v144, s[22:23]
	s_add_i32 m0, s51, 0x2000
	s_nop 0
	global_load_lds_dwordx4 v132, s[22:23]
	s_barrier
	s_waitcnt lgkmcnt(0)
	v_mfma_f32_16x16x32_bf16 v[116:119], v[208:211], v[160:163], v[116:119]
	v_mfma_f32_16x16x32_bf16 v[112:115], v[216:219], v[160:163], v[112:115]
	v_mfma_f32_16x16x32_bf16 v[100:103], v[208:211], v[168:171], v[100:103]
	v_mfma_f32_16x16x32_bf16 v[96:99], v[216:219], v[168:171], v[96:99]
	v_mfma_f32_16x16x32_bf16 v[84:87], v[208:211], v[176:179], v[84:87]
	v_mfma_f32_16x16x32_bf16 v[80:83], v[216:219], v[176:179], v[80:83]
	v_mfma_f32_16x16x32_bf16 v[68:71], v[208:211], v[200:203], v[68:71]
	v_mfma_f32_16x16x32_bf16 v[64:67], v[216:219], v[200:203], v[64:67]
	v_mfma_f32_16x16x32_bf16 v[116:119], v[212:215], v[164:167], v[116:119]
	v_mfma_f32_16x16x32_bf16 v[112:115], v[220:223], v[164:167], v[112:115]
	v_mfma_f32_16x16x32_bf16 v[100:103], v[212:215], v[172:175], v[100:103]
	v_mfma_f32_16x16x32_bf16 v[96:99], v[220:223], v[172:175], v[96:99]
	v_mfma_f32_16x16x32_bf16 v[84:87], v[212:215], v[196:199], v[84:87]
	v_mfma_f32_16x16x32_bf16 v[80:83], v[220:223], v[196:199], v[80:83]
	v_mfma_f32_16x16x32_bf16 v[68:71], v[212:215], v[204:207], v[68:71]
	v_mfma_f32_16x16x32_bf16 v[64:67], v[220:223], v[204:207], v[64:67]
	s_mov_b32 m0, s39
	s_add_u32 s100, s28, s0
	s_addc_u32 s101, s29, s1
	s_barrier
	ds_read_b128 v[160:163], v147 offset:16384
	ds_read_b128 v[164:167], v147 offset:17408
	ds_read_b128 v[168:171], v147 offset:18432
	ds_read_b128 v[172:175], v147 offset:19456
	ds_read_b128 v[176:179], v147 offset:20480
	ds_read_b128 v[196:199], v147 offset:21504
	ds_read_b128 v[200:203], v147 offset:22528
	ds_read_b128 v[204:207], v147 offset:23552
	global_load_lds_dwordx4 v128, s[28:29]
	s_mov_b32 m0, s40
	s_nop 0
	global_load_lds_dwordx4 v130, s[28:29]
	s_barrier
	s_waitcnt lgkmcnt(0)
	v_mfma_f32_16x16x32_bf16 v[60:63], v[138:141], v[160:163], v[60:63]
	v_mfma_f32_16x16x32_bf16 v[56:59], v[152:155], v[160:163], v[56:59]
	v_mfma_f32_16x16x32_bf16 v[44:47], v[138:141], v[168:171], v[44:47]
	v_mfma_f32_16x16x32_bf16 v[40:43], v[152:155], v[168:171], v[40:43]
	v_mfma_f32_16x16x32_bf16 v[28:31], v[138:141], v[176:179], v[28:31]
	v_mfma_f32_16x16x32_bf16 v[24:27], v[152:155], v[176:179], v[24:27]
	v_mfma_f32_16x16x32_bf16 v[12:15], v[138:141], v[200:203], v[12:15]
	v_mfma_f32_16x16x32_bf16 v[8:11], v[152:155], v[200:203], v[8:11]
	v_mfma_f32_16x16x32_bf16 v[60:63], v[148:151], v[164:167], v[60:63]
	v_mfma_f32_16x16x32_bf16 v[56:59], v[156:159], v[164:167], v[56:59]
	v_mfma_f32_16x16x32_bf16 v[44:47], v[148:151], v[172:175], v[44:47]
	v_mfma_f32_16x16x32_bf16 v[40:43], v[156:159], v[172:175], v[40:43]
	v_mfma_f32_16x16x32_bf16 v[28:31], v[148:151], v[196:199], v[28:31]
	v_mfma_f32_16x16x32_bf16 v[24:27], v[156:159], v[196:199], v[24:27]
	v_mfma_f32_16x16x32_bf16 v[12:15], v[148:151], v[204:207], v[12:15]
	v_mfma_f32_16x16x32_bf16 v[8:11], v[156:159], v[204:207], v[8:11]
	s_barrier
	s_add_u32 s52, s22, 0x100000
	s_addc_u32 s53, s23, 0
	s_add_i32 s51, s54, s38
	s_mov_b32 m0, s51
	s_nop 0
	global_load_lds_dwordx4 v144, s[52:53]
	s_add_i32 m0, s51, 0x2000
	s_nop 0
	global_load_lds_dwordx4 v132, s[52:53]
	s_waitcnt vmcnt(6)
	s_barrier
; #define PG8_STAGE(bufoff, gbase, voff) do { _Pragma("unroll") for (int _i = 0; _i < 2; ++_i) \
;     __builtin_amdgcn_global_load_lds((const unsigned*)((const char*)(gbase) + (voff)[_i]), (LAS unsigned*)(lds + (bufoff) + ldsw + _i * 8192), 16, 0, 0); } while (0)
; #define PG8_LDA(dst, b, h) do { _Pragma("unroll") for (int m = 0; m < 4; ++m) _Pragma("unroll") for (int k = 0; k < 2; ++k) dst[m][k] = *(const LAS bf16x8*)(lds + PG8_SA(b, h) + aoff + m * 2048 + k * 1024); } while (0)
; #define PG8_LDB(dst, b, h) do { _Pragma("unroll") for (int n = 0; n < 2; ++n) _Pragma("unroll") for (int k = 0; k < 2; ++k) dst[n][k] = *(const LAS bf16x8*)(lds + PG8_SB(b, h) + boff + n * 2048 + k * 1024); } while (0)
; #define PG8_MMA(ai, bj, At, Bt) do { __builtin_amdgcn_s_setprio(1); _Pragma("unroll") for (int m = 0; m < 4; ++m) _Pragma("unroll") for (int n = 0; n < 2; ++n) _Pragma("unroll") for (int k = 0; k < 2; ++k) \
;     acc[ai][bj][m][n] = __builtin_amdgcn_mfma_f32_16x16x32_bf16(Bt[n][k], At[m][k], acc[ai][bj][m][n], 0, 0, 0); __builtin_amdgcn_s_setprio(0); } while (0)
; #define PG8_WAIT_L(n) asm volatile("s_waitcnt lgkmcnt(" #n ")" ::: "memory")
; #define PG8_BAR __builtin_amdgcn_s_barrier()
; #define PG8_SCHED __builtin_amdgcn_sched_barrier(0)
; template <class Epi, class Sched>
; DI void gemm_phase(LAS unsigned char* lds, const Gemm g, const Sched& S, const Epi& E) {
;     ...
;       PG8_LDB(B0, 1, 0); PG8_SCHED; PG8_LDA(At, 1, 0); PG8_STAGE(PG8_SA(0, 1), a2 + hstep, voffA);
;       PG8_WAIT_L(8); PG8_BAR; PG8_WAIT_L(0); PG8_MMA(0, 0, At, B0); PG8_BAR; PG8_SCHED;
;       PG8_LDB(B1, 1, 1); PG8_STAGE(PG8_SB(1, 0), b3, voffB);
;       PG8_BAR; PG8_WAIT_L(0); PG8_MMA(0, 1, At, B1); PG8_BAR;
;       PG8_LDA(At, 1, 1); PG8_STAGE(PG8_SA(1, 0), a3, voffA);
;       PG8_BAR; PG8_WAIT_L(0); PG8_MMA(1, 0, At, B0); PG8_BAR; PG8_SCHED;
	v_mfma_f32_16x16x32_bf16 v[52:55], v[208:211], v[160:163], v[52:55]
	v_mfma_f32_16x16x32_bf16 v[48:51], v[216:219], v[160:163], v[48:51]
	v_mfma_f32_16x16x32_bf16 v[36:39], v[208:211], v[168:171], v[36:39]
	v_mfma_f32_16x16x32_bf16 v[32:35], v[216:219], v[168:171], v[32:35]
	v_mfma_f32_16x16x32_bf16 v[20:23], v[208:211], v[176:179], v[20:23]
	v_mfma_f32_16x16x32_bf16 v[16:19], v[216:219], v[176:179], v[16:19]
	v_mfma_f32_16x16x32_bf16 v[4:7], v[208:211], v[200:203], v[4:7]
	v_mfma_f32_16x16x32_bf16 v[0:3], v[216:219], v[200:203], v[0:3]
	v_mfma_f32_16x16x32_bf16 v[52:55], v[212:215], v[164:167], v[52:55]
	v_mfma_f32_16x16x32_bf16 v[48:51], v[220:223], v[164:167], v[48:51]
	v_mfma_f32_16x16x32_bf16 v[36:39], v[212:215], v[172:175], v[36:39]
	v_mfma_f32_16x16x32_bf16 v[32:35], v[220:223], v[172:175], v[32:35]
	v_mfma_f32_16x16x32_bf16 v[20:23], v[212:215], v[196:199], v[20:23]
	v_mfma_f32_16x16x32_bf16 v[16:19], v[220:223], v[196:199], v[16:19]
	v_mfma_f32_16x16x32_bf16 v[4:7], v[212:215], v[204:207], v[4:7]
	v_mfma_f32_16x16x32_bf16 v[0:3], v[220:223], v[204:207], v[0:3]
	s_add_i32 s51, 0, 0x18000
	s_barrier
	ds_read_b128 v[138:141], v226
	ds_read_b128 v[148:151], v226 offset:1024
	ds_read_b128 v[152:155], v226 offset:2048
	ds_read_b128 v[156:159], v226 offset:3072
	s_add_u32 s28, s28, 0x100000
	s_addc_u32 s29, s29, 0
	s_mov_b32 m0, s41
	ds_read_b128 v[160:163], v147 offset:32768
	ds_read_b128 v[164:167], v147 offset:33792
	ds_read_b128 v[168:171], v147 offset:34816
	ds_read_b128 v[172:175], v147 offset:35840
	ds_read_b128 v[176:179], v147 offset:36864
	ds_read_b128 v[196:199], v147 offset:37888
	ds_read_b128 v[200:203], v147 offset:38912
	ds_read_b128 v[204:207], v147 offset:39936
	global_load_lds_dwordx4 v128, s[28:29]
	s_mov_b32 m0, s42
	s_nop 0
	global_load_lds_dwordx4 v130, s[28:29]
	s_waitcnt lgkmcnt(8)
	s_barrier
	s_waitcnt lgkmcnt(0)
	v_mfma_f32_16x16x32_bf16 v[124:127], v[138:141], v[160:163], v[124:127]
	v_mfma_f32_16x16x32_bf16 v[120:123], v[152:155], v[160:163], v[120:123]
	v_mfma_f32_16x16x32_bf16 v[108:111], v[138:141], v[168:171], v[108:111]
	v_mfma_f32_16x16x32_bf16 v[104:107], v[152:155], v[168:171], v[104:107]
	v_mfma_f32_16x16x32_bf16 v[92:95], v[138:141], v[176:179], v[92:95]
	v_mfma_f32_16x16x32_bf16 v[88:91], v[152:155], v[176:179], v[88:91]
	v_mfma_f32_16x16x32_bf16 v[76:79], v[138:141], v[200:203], v[76:79]
	v_mfma_f32_16x16x32_bf16 v[72:75], v[152:155], v[200:203], v[72:75]
	v_mfma_f32_16x16x32_bf16 v[124:127], v[148:151], v[164:167], v[124:127]
	v_mfma_f32_16x16x32_bf16 v[120:123], v[156:159], v[164:167], v[120:123]
	v_mfma_f32_16x16x32_bf16 v[108:111], v[148:151], v[172:175], v[108:111]
	v_mfma_f32_16x16x32_bf16 v[104:107], v[156:159], v[172:175], v[104:107]
	v_mfma_f32_16x16x32_bf16 v[92:95], v[148:151], v[196:199], v[92:95]
	v_mfma_f32_16x16x32_bf16 v[88:91], v[156:159], v[196:199], v[88:91]
	v_mfma_f32_16x16x32_bf16 v[76:79], v[148:151], v[204:207], v[76:79]
	v_mfma_f32_16x16x32_bf16 v[72:75], v[156:159], v[204:207], v[72:75]
	s_barrier
	s_add_i32 s28, 0, 0x1c000
	s_add_i32 s29, s51, s38
	s_mov_b32 m0, s29
	ds_read_b128 v[208:211], v227
	ds_read_b128 v[212:215], v227 offset:1024
	ds_read_b128 v[216:219], v227 offset:2048
	ds_read_b128 v[220:223], v227 offset:3072
	global_load_lds_dwordx4 v144, vcc
	s_add_i32 m0, s29, 0x2000
	s_nop 0
	global_load_lds_dwordx4 v132, vcc
	s_barrier
	s_waitcnt lgkmcnt(0)
	v_mfma_f32_16x16x32_bf16 v[116:119], v[208:211], v[160:163], v[116:119]
	v_mfma_f32_16x16x32_bf16 v[112:115], v[216:219], v[160:163], v[112:115]
	v_mfma_f32_16x16x32_bf16 v[100:103], v[208:211], v[168:171], v[100:103]
	v_mfma_f32_16x16x32_bf16 v[96:99], v[216:219], v[168:171], v[96:99]
	v_mfma_f32_16x16x32_bf16 v[84:87], v[208:211], v[176:179], v[84:87]
	v_mfma_f32_16x16x32_bf16 v[80:83], v[216:219], v[176:179], v[80:83]
	v_mfma_f32_16x16x32_bf16 v[68:71], v[208:211], v[200:203], v[68:71]
	v_mfma_f32_16x16x32_bf16 v[64:67], v[216:219], v[200:203], v[64:67]
	v_mfma_f32_16x16x32_bf16 v[116:119], v[212:215], v[164:167], v[116:119]
	v_mfma_f32_16x16x32_bf16 v[112:115], v[220:223], v[164:167], v[112:115]
	v_mfma_f32_16x16x32_bf16 v[100:103], v[212:215], v[172:175], v[100:103]
	v_mfma_f32_16x16x32_bf16 v[96:99], v[220:223], v[172:175], v[96:99]
	v_mfma_f32_16x16x32_bf16 v[84:87], v[212:215], v[196:199], v[84:87]
	v_mfma_f32_16x16x32_bf16 v[80:83], v[220:223], v[196:199], v[80:83]
	v_mfma_f32_16x16x32_bf16 v[68:71], v[212:215], v[204:207], v[68:71]
	v_mfma_f32_16x16x32_bf16 v[64:67], v[220:223], v[204:207], v[64:67]
	s_mov_b32 m0, s46
	s_barrier
	ds_read_b128 v[160:163], v147 offset:49152
	ds_read_b128 v[164:167], v147 offset:50176
	ds_read_b128 v[168:171], v147 offset:51200
	ds_read_b128 v[172:175], v147 offset:52224
	ds_read_b128 v[176:179], v147 offset:53248
	ds_read_b128 v[196:199], v147 offset:54272
	ds_read_b128 v[200:203], v147 offset:55296
	ds_read_b128 v[204:207], v147 offset:56320
	global_load_lds_dwordx4 v128, s[100:101]
	s_mov_b32 m0, s47
	s_nop 0
	global_load_lds_dwordx4 v130, s[100:101]
	s_barrier
	s_waitcnt lgkmcnt(0)
	v_mfma_f32_16x16x32_bf16 v[60:63], v[138:141], v[160:163], v[60:63]
	v_mfma_f32_16x16x32_bf16 v[56:59], v[152:155], v[160:163], v[56:59]
	v_mfma_f32_16x16x32_bf16 v[44:47], v[138:141], v[168:171], v[44:47]
	v_mfma_f32_16x16x32_bf16 v[40:43], v[152:155], v[168:171], v[40:43]
	v_mfma_f32_16x16x32_bf16 v[28:31], v[138:141], v[176:179], v[28:31]
	v_mfma_f32_16x16x32_bf16 v[24:27], v[152:155], v[176:179], v[24:27]
	v_mfma_f32_16x16x32_bf16 v[12:15], v[138:141], v[200:203], v[12:15]
	v_mfma_f32_16x16x32_bf16 v[8:11], v[152:155], v[200:203], v[8:11]
	v_mfma_f32_16x16x32_bf16 v[60:63], v[148:151], v[164:167], v[60:63]
	v_mfma_f32_16x16x32_bf16 v[56:59], v[156:159], v[164:167], v[56:59]
	v_mfma_f32_16x16x32_bf16 v[44:47], v[148:151], v[172:175], v[44:47]
	v_mfma_f32_16x16x32_bf16 v[40:43], v[156:159], v[172:175], v[40:43]
	v_mfma_f32_16x16x32_bf16 v[28:31], v[148:151], v[196:199], v[28:31]
	v_mfma_f32_16x16x32_bf16 v[24:27], v[156:159], v[196:199], v[24:27]
	v_mfma_f32_16x16x32_bf16 v[12:15], v[148:151], v[204:207], v[12:15]
	v_mfma_f32_16x16x32_bf16 v[8:11], v[156:159], v[204:207], v[8:11]
	s_barrier
; template <class Epi, class Sched>
; DI void gemm_phase(LAS unsigned char* lds, const Gemm g, const Sched& S, const Epi& E) {
;     ...
;       PG8_STAGE(PG8_SB(1, 1), b3 + hstep, voffB);
;       PG8_WAIT_V(6); PG8_BAR; PG8_MMA(1, 1, At, B1); PG8_BAR;
;   DI void operator()(const f32x4 (&acc)[2][2][4][2], const pg8::Unit& u, int wr, int wc, int fr_, int fq_) const {
;     ...
;             } else if (EPI == EPI_RESID) {
;               if (n == 0) {
;                 const int f8 = u.pn * 256 + bj * 128 + wc * 32 + 8 * fq;
;                 const f32x4 v1 = acc[ai][bj][m][1];
;                 f32x4 r0, r1;
;                 if (rsrc) {
;                   r0 = *(const f32x4*)(rsrc + (size_t)token * 1024 + f8); r1 = *(const f32x4*)(rsrc + (size_t)token * 1024 + f8 + 4);
;                 } else {
;                   const u32x4 xu = *(const u32x4*)(xr + (size_t)token * 1024 + f8);
;                   r0 = (f32x4){bf2f(xu.x & 0xffffu), bf2f(xu.x >> 16), bf2f(xu.y & 0xffffu), bf2f(xu.y >> 16)};
;                   r1 = (f32x4){bf2f(xu.z & 0xffffu), bf2f(xu.z >> 16), bf2f(xu.w & 0xffffu), bf2f(xu.w >> 16)};
;                 }
;                 r0 += v; r1 += v1;
;                 st_bf8(xr + (size_t)token * 1024 + f8, r0, r1, 1.f);
;                 ssq += r0[0] * r0[0] + r0[1] * r0[1] + r0[2] * r0[2] + r0[3] * r0[3] + r1[0] * r1[0] + r1[1] * r1[1] + r1[2] * r1[2] + r1[3] * r1[3];
;               }
;             } else {
;               if (n == 0) {
;                 const f32x4 v1 = acc[ai][bj][m][1];
;                 u32x4 o4;
;                 { const float t0 = fmaxf(v[0], 0.f) * rinv, t1 = fmaxf(v[1], 0.f) * rinv, t2 = fmaxf(v[2], 0.f) * rinv, t3 = fmaxf(v[3], 0.f) * rinv;
;                   o4.x = pack2(t0 * t0, t1 * t1); o4.y = pack2(t2 * t2, t3 * t3); }
;                 { const float t0 = fmaxf(v1[0], 0.f) * rinv, t1 = fmaxf(v1[1], 0.f) * rinv, t2 = fmaxf(v1[2], 0.f) * rinv, t3 = fmaxf(v1[3], 0.f) * rinv;
;                   o4.z = pack2(t0 * t0, t1 * t1); o4.w = pack2(t2 * t2, t3 * t3); }
;                 *(u32x4*)((u16*)big + (size_t)token * 4096 + u.pn * 256 + bj * 128 + wc * 32 + 8 * fq) = o4;
;               }
;             }
;           }
;         if (EPI == EPI_RESID) {
;           ssq += shx(ssq, 16, t_ & 63);
;           ssq += shx(ssq, 32, t_ & 63);
;           if (fq == 0) ss_out[(size_t)token * 16 + u.pn * 4 + wc] = ssq;
	s_add_u32 s22, s22, 0x100080
	s_addc_u32 s23, s23, 0
	s_add_i32 s28, s28, s38
	s_mov_b32 m0, s28
	s_nop 0
	global_load_lds_dwordx4 v144, s[22:23]
	s_add_i32 m0, s28, 0x2000
	s_nop 0
	global_load_lds_dwordx4 v132, s[22:23]
	s_waitcnt vmcnt(6)
	s_barrier
	v_mfma_f32_16x16x32_bf16 v[52:55], v[208:211], v[160:163], v[52:55]
	v_mfma_f32_16x16x32_bf16 v[48:51], v[216:219], v[160:163], v[48:51]
	v_mfma_f32_16x16x32_bf16 v[36:39], v[208:211], v[168:171], v[36:39]
	v_mfma_f32_16x16x32_bf16 v[32:35], v[216:219], v[168:171], v[32:35]
	v_mfma_f32_16x16x32_bf16 v[20:23], v[208:211], v[176:179], v[20:23]
	v_mfma_f32_16x16x32_bf16 v[16:19], v[216:219], v[176:179], v[16:19]
	v_mfma_f32_16x16x32_bf16 v[4:7], v[208:211], v[200:203], v[4:7]
	v_mfma_f32_16x16x32_bf16 v[0:3], v[216:219], v[200:203], v[0:3]
	v_mfma_f32_16x16x32_bf16 v[52:55], v[212:215], v[164:167], v[52:55]
	v_mfma_f32_16x16x32_bf16 v[48:51], v[220:223], v[164:167], v[48:51]
	v_mfma_f32_16x16x32_bf16 v[36:39], v[212:215], v[172:175], v[36:39]
	v_mfma_f32_16x16x32_bf16 v[32:35], v[220:223], v[172:175], v[32:35]
	v_mfma_f32_16x16x32_bf16 v[20:23], v[212:215], v[196:199], v[20:23]
	v_mfma_f32_16x16x32_bf16 v[16:19], v[220:223], v[196:199], v[16:19]
	v_mfma_f32_16x16x32_bf16 v[4:7], v[212:215], v[204:207], v[4:7]
	v_mfma_f32_16x16x32_bf16 v[0:3], v[220:223], v[204:207], v[0:3]
	s_add_i32 s50, s50, 2
	s_add_u32 s20, s20, 0x100
	s_addc_u32 s21, s21, 0
	s_add_u32 s24, s24, 0x100
	s_addc_u32 s49, s49, 0
	s_cmp_gt_u32 s50, 61
	s_barrier
	s_cbranch_scc0 .LBB0_1905
	s_lshl_b32 s7, s18, 8
	v_mov_b32_e32 v139, v182
	s_add_i32 s7, s7, s44
	s_nop 0
	v_and_or_b32 v140, v139, 15, s7
	s_lshl_b32 s7, s16, 8
	v_bfe_u32 v141, v139, 4, 2
	s_or_b32 s7, s7, s45
	v_lshl_or_b32 v138, v141, 3, s7
	v_cmp_eq_u32_e32 vcc, 0, v141
	v_ashrrev_i32_e32 v141, 31, v140
	v_lshlrev_b32_e32 v139, 2, v139
	s_movk_i32 s7, 0x80
	v_lshlrev_b64 v[142:143], 11, v[140:141]
	v_bitop3_b32 v149, v139, 64, v190 bitop3:0x6c
	v_bitop3_b32 v148, v139, s7, v190 bitop3:0x6c
	v_ashrrev_i32_e32 v139, 31, v138
	v_lshl_add_u64 v[142:143], s[4:5], 0, v[142:143]
	v_lshl_add_u64 v[142:143], v[138:139], 1, v[142:143]
	v_lshlrev_b32_e32 v250, 1, v138
	v_lshl_add_u32 v250, v140, 11, v250
	global_load_dwordx4 v[158:161], v250, s[4:5]
	global_load_dwordx4 v[162:165], v250, s[4:5] offset:256
	v_add_u32_e32 v250, 0x8000, v250
	global_load_dwordx4 v[166:169], v250, s[4:5]
	global_load_dwordx4 v[170:173], v250, s[4:5] offset:256
	v_add_u32_e32 v250, 0x8000, v250
	global_load_dwordx4 v[174:177], v250, s[4:5]
	global_load_dwordx4 v[178:181], v250, s[4:5] offset:256
	v_add_u32_e32 v250, 0x8000, v250
	global_load_dwordx4 v[196:199], v250, s[4:5]
	global_load_dwordx4 v[200:203], v250, s[4:5] offset:256
	v_add_u32_e32 v250, 0x28000, v250
	global_load_dwordx4 v[204:207], v250, s[4:5]
	global_load_dwordx4 v[208:211], v250, s[4:5] offset:256
	v_add_u32_e32 v250, 0x8000, v250
	global_load_dwordx4 v[212:215], v250, s[4:5]
	global_load_dwordx4 v[216:219], v250, s[4:5] offset:256
	v_add_u32_e32 v250, 0x8000, v250
	global_load_dwordx4 v[220:223], v250, s[4:5]
	global_load_dwordx4 v[224:227], v250, s[4:5] offset:256
	v_add_u32_e32 v250, 0x8000, v250
	global_load_dwordx4 v[228:231], v250, s[4:5]
	global_load_dwordx4 v[232:235], v250, s[4:5] offset:256
	s_lshl_b32 s16, s16, 2
	s_ashr_i32 s17, s16, 31
	s_waitcnt vmcnt(0)
	v_lshlrev_b32_e32 v154, 16, v158
	v_and_b32_e32 v155, 0xffff0000, v158
	v_lshlrev_b32_e32 v150, 16, v159
	v_and_b32_e32 v151, 0xffff0000, v159
	v_lshlrev_b32_e32 v156, 16, v160
	v_and_b32_e32 v157, 0xffff0000, v160
	v_lshlrev_b32_e32 v152, 16, v161
	v_and_b32_e32 v153, 0xffff0000, v161
	v_pk_add_f32 v[126:127], v[126:127], v[150:151]
	v_pk_add_f32 v[124:125], v[124:125], v[154:155]
	v_pk_add_f32 v[150:151], v[122:123], v[152:153]
	v_pk_add_f32 v[152:153], v[120:121], v[156:157]
	v_cvt_pk_bf16_f32 v120, v124, v125
	v_cvt_pk_bf16_f32 v121, v126, v127
	v_cvt_pk_bf16_f32 v122, v152, v153
	v_cvt_pk_bf16_f32 v123, v150, v151
	global_store_dwordx4 v[142:143], v[120:123], off
	v_mul_f32_e32 v154, v125, v125
	v_fmac_f32_e32 v154, v124, v124
	v_fmac_f32_e32 v154, v126, v126
	v_fmac_f32_e32 v154, v127, v127
	v_fmac_f32_e32 v154, v152, v152
	v_fmac_f32_e32 v154, v153, v153
	v_fmac_f32_e32 v154, v150, v150
	v_fmac_f32_e32 v154, v151, v151
	v_lshlrev_b32_e32 v124, 16, v162
	v_and_b32_e32 v125, 0xffff0000, v162
	v_lshlrev_b32_e32 v120, 16, v163
	v_and_b32_e32 v121, 0xffff0000, v163
	v_lshlrev_b32_e32 v126, 16, v164
	v_and_b32_e32 v127, 0xffff0000, v164
	v_lshlrev_b32_e32 v122, 16, v165
	v_and_b32_e32 v123, 0xffff0000, v165
	v_pk_add_f32 v[118:119], v[118:119], v[120:121]
	v_pk_add_f32 v[116:117], v[116:117], v[124:125]
	v_pk_add_f32 v[120:121], v[114:115], v[122:123]
	v_pk_add_f32 v[122:123], v[112:113], v[126:127]
	v_cvt_pk_bf16_f32 v112, v116, v117
	v_cvt_pk_bf16_f32 v113, v118, v119
	v_cvt_pk_bf16_f32 v114, v122, v123
	v_cvt_pk_bf16_f32 v115, v120, v121
	global_store_dwordx4 v[142:143], v[112:115], off offset:256
	s_nop 1
	v_mul_f32_e32 v112, v117, v117
	v_fmac_f32_e32 v112, v116, v116
	v_fmac_f32_e32 v112, v118, v118
	v_fmac_f32_e32 v112, v119, v119
	v_fmac_f32_e32 v112, v122, v122
	v_fmac_f32_e32 v112, v123, v123
	v_fmac_f32_e32 v112, v120, v120
	v_fmac_f32_e32 v112, v121, v121
	v_add_f32_e32 v112, v154, v112
	v_mov_b32_e32 v236, v112
	v_or_b32_e32 v112, 16, v140
	s_waitcnt lgkmcnt(0)
; DI float bf2f(unsigned v) { return __uint_as_float(v << 16); }
;   DI void operator()(const f32x4 (&acc)[2][2][4][2], const pg8::Unit& u, int wr, int wc, int fr_, int fq_) const {
;     ...
;             } else if (EPI == EPI_RESID) {
;               if (n == 0) {
;                 const int f8 = u.pn * 256 + bj * 128 + wc * 32 + 8 * fq;
;                 const f32x4 v1 = acc[ai][bj][m][1];
;                 f32x4 r0, r1;
;                 if (rsrc) {
;                   r0 = *(const f32x4*)(rsrc + (size_t)token * 1024 + f8); r1 = *(const f32x4*)(rsrc + (size_t)token * 1024 + f8 + 4);
;                 } else {
;                   const u32x4 xu = *(const u32x4*)(xr + (size_t)token * 1024 + f8);
;                   r0 = (f32x4){bf2f(xu.x & 0xffffu), bf2f(xu.x >> 16), bf2f(xu.y & 0xffffu), bf2f(xu.y >> 16)};
;                   r1 = (f32x4){bf2f(xu.z & 0xffffu), bf2f(xu.z >> 16), bf2f(xu.w & 0xffffu), bf2f(xu.w >> 16)};
;                 }
;                 r0 += v; r1 += v1;
;                 st_bf8(xr + (size_t)token * 1024 + f8, r0, r1, 1.f);
;                 ssq += r0[0] * r0[0] + r0[1] * r0[1] + r0[2] * r0[2] + r0[3] * r0[3] + r1[0] * r1[0] + r1[1] * r1[1] + r1[2] * r1[2] + r1[3] * r1[3];
;               }
;             } else {
;               if (n == 0) {
;                 const f32x4 v1 = acc[ai][bj][m][1];
;                 u32x4 o4;
;                 { const float t0 = fmaxf(v[0], 0.f) * rinv, t1 = fmaxf(v[1], 0.f) * rinv, t2 = fmaxf(v[2], 0.f) * rinv, t3 = fmaxf(v[3], 0.f) * rinv;
;                   o4.x = pack2(t0 * t0, t1 * t1); o4.y = pack2(t2 * t2, t3 * t3); }
;                 { const float t0 = fmaxf(v1[0], 0.f) * rinv, t1 = fmaxf(v1[1], 0.f) * rinv, t2 = fmaxf(v1[2], 0.f) * rinv, t3 = fmaxf(v1[3], 0.f) * rinv;
;                   o4.z = pack2(t0 * t0, t1 * t1); o4.w = pack2(t2 * t2, t3 * t3); }
;                 *(u32x4*)((u16*)big + (size_t)token * 4096 + u.pn * 256 + bj * 128 + wc * 32 + 8 * fq) = o4;
;               }
;             }
;           }
;         if (EPI == EPI_RESID) {
;           ssq += shx(ssq, 16, t_ & 63);
;           ssq += shx(ssq, 32, t_ & 63);
;           if (fq == 0) ss_out[(size_t)token * 16 + u.pn * 4 + wc] = ssq;
	v_ashrrev_i32_e32 v113, 31, v112
	v_lshlrev_b64 v[114:115], 11, v[112:113]
	v_lshl_add_u64 v[114:115], s[4:5], 0, v[114:115]
	v_lshl_add_u64 v[118:119], v[138:139], 1, v[114:115]
	v_lshlrev_b32_e32 v120, 16, v166
	v_and_b32_e32 v121, 0xffff0000, v166
	v_lshlrev_b32_e32 v114, 16, v167
	v_and_b32_e32 v115, 0xffff0000, v167
	v_lshlrev_b32_e32 v122, 16, v168
	v_and_b32_e32 v123, 0xffff0000, v168
	v_lshlrev_b32_e32 v116, 16, v169
	v_and_b32_e32 v117, 0xffff0000, v169
	v_pk_add_f32 v[110:111], v[110:111], v[114:115]
	v_pk_add_f32 v[108:109], v[108:109], v[120:121]
	v_pk_add_f32 v[114:115], v[106:107], v[116:117]
	v_pk_add_f32 v[116:117], v[104:105], v[122:123]
	v_cvt_pk_bf16_f32 v104, v108, v109
	v_cvt_pk_bf16_f32 v105, v110, v111
	v_cvt_pk_bf16_f32 v106, v116, v117
	v_cvt_pk_bf16_f32 v107, v114, v115
	global_store_dwordx4 v[118:119], v[104:107], off
	v_mul_f32_e32 v120, v109, v109
	v_fmac_f32_e32 v120, v108, v108
	v_fmac_f32_e32 v120, v110, v110
	v_fmac_f32_e32 v120, v111, v111
	v_fmac_f32_e32 v120, v116, v116
	v_fmac_f32_e32 v120, v117, v117
	v_fmac_f32_e32 v120, v114, v114
	v_fmac_f32_e32 v120, v115, v115
	v_lshlrev_b32_e32 v108, 16, v170
	v_and_b32_e32 v109, 0xffff0000, v170
	v_lshlrev_b32_e32 v104, 16, v171
	v_and_b32_e32 v105, 0xffff0000, v171
	v_lshlrev_b32_e32 v110, 16, v172
	v_and_b32_e32 v111, 0xffff0000, v172
	v_lshlrev_b32_e32 v106, 16, v173
	v_and_b32_e32 v107, 0xffff0000, v173
	v_pk_add_f32 v[102:103], v[102:103], v[104:105]
	v_pk_add_f32 v[100:101], v[100:101], v[108:109]
	v_pk_add_f32 v[104:105], v[98:99], v[106:107]
	v_pk_add_f32 v[106:107], v[96:97], v[110:111]
	v_cvt_pk_bf16_f32 v96, v100, v101
	v_cvt_pk_bf16_f32 v97, v102, v103
	v_cvt_pk_bf16_f32 v98, v106, v107
	v_cvt_pk_bf16_f32 v99, v104, v105
	global_store_dwordx4 v[118:119], v[96:99], off offset:256
	s_nop 1
	v_mul_f32_e32 v96, v101, v101
	v_fmac_f32_e32 v96, v100, v100
	v_fmac_f32_e32 v96, v102, v102
	v_fmac_f32_e32 v96, v103, v103
	v_fmac_f32_e32 v96, v106, v106
	v_fmac_f32_e32 v96, v107, v107
	v_fmac_f32_e32 v96, v104, v104
	v_fmac_f32_e32 v96, v105, v105
	v_add_f32_e32 v96, v120, v96
	v_mov_b32_e32 v242, v96
	v_or_b32_e32 v96, 32, v140
	s_waitcnt lgkmcnt(0)
	v_ashrrev_i32_e32 v97, 31, v96
	v_lshlrev_b64 v[98:99], 11, v[96:97]
	v_lshl_add_u64 v[98:99], s[4:5], 0, v[98:99]
	v_lshl_add_u64 v[102:103], v[138:139], 1, v[98:99]
	v_lshlrev_b32_e32 v104, 16, v174
	v_and_b32_e32 v105, 0xffff0000, v174
	v_lshlrev_b32_e32 v98, 16, v175
	v_and_b32_e32 v99, 0xffff0000, v175
	v_lshlrev_b32_e32 v106, 16, v176
	v_and_b32_e32 v107, 0xffff0000, v176
	v_lshlrev_b32_e32 v100, 16, v177
	v_and_b32_e32 v101, 0xffff0000, v177
	v_pk_add_f32 v[94:95], v[94:95], v[98:99]
	v_pk_add_f32 v[92:93], v[92:93], v[104:105]
	v_pk_add_f32 v[98:99], v[90:91], v[100:101]
	v_pk_add_f32 v[100:101], v[88:89], v[106:107]
	v_cvt_pk_bf16_f32 v88, v92, v93
	v_cvt_pk_bf16_f32 v89, v94, v95
	v_cvt_pk_bf16_f32 v90, v100, v101
	v_cvt_pk_bf16_f32 v91, v98, v99
	global_store_dwordx4 v[102:103], v[88:91], off
	v_mul_f32_e32 v104, v93, v93
	v_fmac_f32_e32 v104, v92, v92
	v_fmac_f32_e32 v104, v94, v94
	v_fmac_f32_e32 v104, v95, v95
	v_fmac_f32_e32 v104, v100, v100
	v_fmac_f32_e32 v104, v101, v101
	v_fmac_f32_e32 v104, v98, v98
	v_fmac_f32_e32 v104, v99, v99
	v_lshlrev_b32_e32 v92, 16, v178
	v_and_b32_e32 v93, 0xffff0000, v178
	v_lshlrev_b32_e32 v88, 16, v179
	v_and_b32_e32 v89, 0xffff0000, v179
	v_lshlrev_b32_e32 v94, 16, v180
	v_and_b32_e32 v95, 0xffff0000, v180
	v_lshlrev_b32_e32 v90, 16, v181
	v_and_b32_e32 v91, 0xffff0000, v181
	v_pk_add_f32 v[86:87], v[86:87], v[88:89]
	v_pk_add_f32 v[84:85], v[84:85], v[92:93]
	v_pk_add_f32 v[88:89], v[82:83], v[90:91]
	v_pk_add_f32 v[90:91], v[80:81], v[94:95]
	v_cvt_pk_bf16_f32 v80, v84, v85
	v_cvt_pk_bf16_f32 v81, v86, v87
	v_cvt_pk_bf16_f32 v82, v90, v91
	v_cvt_pk_bf16_f32 v83, v88, v89
	global_store_dwordx4 v[102:103], v[80:83], off offset:256
	s_nop 1
	v_mul_f32_e32 v80, v85, v85
	v_fmac_f32_e32 v80, v84, v84
	v_fmac_f32_e32 v80, v86, v86
	v_fmac_f32_e32 v80, v87, v87
	v_fmac_f32_e32 v80, v90, v90
	v_fmac_f32_e32 v80, v91, v91
	v_fmac_f32_e32 v80, v88, v88
	v_fmac_f32_e32 v80, v89, v89
	v_add_f32_e32 v80, v104, v80
	v_mov_b32_e32 v243, v80
	v_or_b32_e32 v80, 48, v140
	s_waitcnt lgkmcnt(0)
	v_ashrrev_i32_e32 v81, 31, v80
	v_lshlrev_b64 v[82:83], 11, v[80:81]
	v_lshl_add_u64 v[82:83], s[4:5], 0, v[82:83]
	v_lshl_add_u64 v[86:87], v[138:139], 1, v[82:83]
	v_lshlrev_b32_e32 v88, 16, v196
	v_and_b32_e32 v89, 0xffff0000, v196
	v_lshlrev_b32_e32 v82, 16, v197
	v_and_b32_e32 v83, 0xffff0000, v197
	v_lshlrev_b32_e32 v90, 16, v198
	v_and_b32_e32 v91, 0xffff0000, v198
	v_lshlrev_b32_e32 v84, 16, v199
	v_and_b32_e32 v85, 0xffff0000, v199
	v_pk_add_f32 v[78:79], v[78:79], v[82:83]
	v_pk_add_f32 v[76:77], v[76:77], v[88:89]
	v_pk_add_f32 v[82:83], v[74:75], v[84:85]
	v_pk_add_f32 v[84:85], v[72:73], v[90:91]
	v_cvt_pk_bf16_f32 v72, v76, v77
	v_cvt_pk_bf16_f32 v73, v78, v79
	v_cvt_pk_bf16_f32 v74, v84, v85
	v_cvt_pk_bf16_f32 v75, v82, v83
	global_store_dwordx4 v[86:87], v[72:75], off
	v_mul_f32_e32 v88, v77, v77
	v_fmac_f32_e32 v88, v76, v76
	v_fmac_f32_e32 v88, v78, v78
	v_fmac_f32_e32 v88, v79, v79
	v_fmac_f32_e32 v88, v84, v84
	v_fmac_f32_e32 v88, v85, v85
	v_fmac_f32_e32 v88, v82, v82
	v_fmac_f32_e32 v88, v83, v83
	v_lshlrev_b32_e32 v76, 16, v200
	v_and_b32_e32 v77, 0xffff0000, v200
	v_lshlrev_b32_e32 v72, 16, v201
	v_and_b32_e32 v73, 0xffff0000, v201
	v_lshlrev_b32_e32 v78, 16, v202
	v_and_b32_e32 v79, 0xffff0000, v202
	v_lshlrev_b32_e32 v74, 16, v203
	v_and_b32_e32 v75, 0xffff0000, v203
	v_pk_add_f32 v[70:71], v[70:71], v[72:73]
	v_pk_add_f32 v[68:69], v[68:69], v[76:77]
	v_pk_add_f32 v[72:73], v[66:67], v[74:75]
	v_pk_add_f32 v[74:75], v[64:65], v[78:79]
	v_cvt_pk_bf16_f32 v64, v68, v69
	v_cvt_pk_bf16_f32 v65, v70, v71
	v_cvt_pk_bf16_f32 v66, v74, v75
	v_cvt_pk_bf16_f32 v67, v72, v73
	global_store_dwordx4 v[86:87], v[64:67], off offset:256
	s_nop 1
	v_mul_f32_e32 v64, v69, v69
	v_fmac_f32_e32 v64, v68, v68
	v_fmac_f32_e32 v64, v70, v70
	v_fmac_f32_e32 v64, v71, v71
	v_fmac_f32_e32 v64, v74, v74
	v_fmac_f32_e32 v64, v75, v75
	v_fmac_f32_e32 v64, v72, v72
	v_fmac_f32_e32 v64, v73, v73
	v_add_f32_e32 v64, v88, v64
	v_mov_b32_e32 v244, v64
	v_readlane_b32 s51, v237, 11
	v_add_u32_e32 v64, 0x80, v140
	s_waitcnt lgkmcnt(0)
; DI float bf2f(unsigned v) { return __uint_as_float(v << 16); }
;   DI void operator()(const f32x4 (&acc)[2][2][4][2], const pg8::Unit& u, int wr, int wc, int fr_, int fq_) const {
;     ...
;             } else if (EPI == EPI_RESID) {
;               if (n == 0) {
;                 const int f8 = u.pn * 256 + bj * 128 + wc * 32 + 8 * fq;
;                 const f32x4 v1 = acc[ai][bj][m][1];
;                 f32x4 r0, r1;
;                 if (rsrc) {
;                   r0 = *(const f32x4*)(rsrc + (size_t)token * 1024 + f8); r1 = *(const f32x4*)(rsrc + (size_t)token * 1024 + f8 + 4);
;                 } else {
;                   const u32x4 xu = *(const u32x4*)(xr + (size_t)token * 1024 + f8);
;                   r0 = (f32x4){bf2f(xu.x & 0xffffu), bf2f(xu.x >> 16), bf2f(xu.y & 0xffffu), bf2f(xu.y >> 16)};
;                   r1 = (f32x4){bf2f(xu.z & 0xffffu), bf2f(xu.z >> 16), bf2f(xu.w & 0xffffu), bf2f(xu.w >> 16)};
;                 }
;                 r0 += v; r1 += v1;
;                 st_bf8(xr + (size_t)token * 1024 + f8, r0, r1, 1.f);
;                 ssq += r0[0] * r0[0] + r0[1] * r0[1] + r0[2] * r0[2] + r0[3] * r0[3] + r1[0] * r1[0] + r1[1] * r1[1] + r1[2] * r1[2] + r1[3] * r1[3];
;               }
;             } else {
;               if (n == 0) {
;                 const f32x4 v1 = acc[ai][bj][m][1];
;                 u32x4 o4;
;                 { const float t0 = fmaxf(v[0], 0.f) * rinv, t1 = fmaxf(v[1], 0.f) * rinv, t2 = fmaxf(v[2], 0.f) * rinv, t3 = fmaxf(v[3], 0.f) * rinv;
;                   o4.x = pack2(t0 * t0, t1 * t1); o4.y = pack2(t2 * t2, t3 * t3); }
;                 { const float t0 = fmaxf(v1[0], 0.f) * rinv, t1 = fmaxf(v1[1], 0.f) * rinv, t2 = fmaxf(v1[2], 0.f) * rinv, t3 = fmaxf(v1[3], 0.f) * rinv;
;                   o4.z = pack2(t0 * t0, t1 * t1); o4.w = pack2(t2 * t2, t3 * t3); }
;                 *(u32x4*)((u16*)big + (size_t)token * 4096 + u.pn * 256 + bj * 128 + wc * 32 + 8 * fq) = o4;
;               }
;             }
;           }
;         if (EPI == EPI_RESID) {
;           ssq += shx(ssq, 16, t_ & 63);
;           ssq += shx(ssq, 32, t_ & 63);
;           if (fq == 0) ss_out[(size_t)token * 16 + u.pn * 4 + wc] = ssq;
	v_ashrrev_i32_e32 v65, 31, v64
	v_lshlrev_b64 v[66:67], 11, v[64:65]
	v_lshl_add_u64 v[66:67], s[4:5], 0, v[66:67]
	v_lshl_add_u64 v[70:71], v[138:139], 1, v[66:67]
	v_lshlrev_b32_e32 v72, 16, v204
	v_and_b32_e32 v73, 0xffff0000, v204
	v_lshlrev_b32_e32 v66, 16, v205
	v_and_b32_e32 v67, 0xffff0000, v205
	v_lshlrev_b32_e32 v74, 16, v206
	v_and_b32_e32 v75, 0xffff0000, v206
	v_lshlrev_b32_e32 v68, 16, v207
	v_and_b32_e32 v69, 0xffff0000, v207
	v_pk_add_f32 v[62:63], v[62:63], v[66:67]
	v_pk_add_f32 v[60:61], v[60:61], v[72:73]
	v_pk_add_f32 v[66:67], v[58:59], v[68:69]
	v_pk_add_f32 v[68:69], v[56:57], v[74:75]
	v_cvt_pk_bf16_f32 v56, v60, v61
	v_cvt_pk_bf16_f32 v57, v62, v63
	v_cvt_pk_bf16_f32 v58, v68, v69
	v_cvt_pk_bf16_f32 v59, v66, v67
	global_store_dwordx4 v[70:71], v[56:59], off
	v_mul_f32_e32 v72, v61, v61
	v_fmac_f32_e32 v72, v60, v60
	v_fmac_f32_e32 v72, v62, v62
	v_fmac_f32_e32 v72, v63, v63
	v_fmac_f32_e32 v72, v68, v68
	v_fmac_f32_e32 v72, v69, v69
	v_fmac_f32_e32 v72, v66, v66
	v_fmac_f32_e32 v72, v67, v67
	v_lshlrev_b32_e32 v60, 16, v208
	v_and_b32_e32 v61, 0xffff0000, v208
	v_lshlrev_b32_e32 v56, 16, v209
	v_and_b32_e32 v57, 0xffff0000, v209
	v_lshlrev_b32_e32 v62, 16, v210
	v_and_b32_e32 v63, 0xffff0000, v210
	v_lshlrev_b32_e32 v58, 16, v211
	v_and_b32_e32 v59, 0xffff0000, v211
	v_pk_add_f32 v[54:55], v[54:55], v[56:57]
	v_pk_add_f32 v[52:53], v[52:53], v[60:61]
	v_pk_add_f32 v[56:57], v[50:51], v[58:59]
	v_pk_add_f32 v[58:59], v[48:49], v[62:63]
	v_cvt_pk_bf16_f32 v48, v52, v53
	v_cvt_pk_bf16_f32 v49, v54, v55
	v_cvt_pk_bf16_f32 v50, v58, v59
	v_cvt_pk_bf16_f32 v51, v56, v57
	global_store_dwordx4 v[70:71], v[48:51], off offset:256
	s_nop 1
	v_mul_f32_e32 v48, v53, v53
	v_fmac_f32_e32 v48, v52, v52
	v_fmac_f32_e32 v48, v54, v54
	v_fmac_f32_e32 v48, v55, v55
	v_fmac_f32_e32 v48, v58, v58
	v_fmac_f32_e32 v48, v59, v59
	v_fmac_f32_e32 v48, v56, v56
	v_fmac_f32_e32 v48, v57, v57
	v_add_f32_e32 v48, v72, v48
	v_mov_b32_e32 v245, v48
	v_add_u32_e32 v48, 0x90, v140
	s_waitcnt lgkmcnt(0)
	v_ashrrev_i32_e32 v49, 31, v48
	v_lshlrev_b64 v[50:51], 11, v[48:49]
	v_lshl_add_u64 v[50:51], s[4:5], 0, v[50:51]
	v_lshl_add_u64 v[54:55], v[138:139], 1, v[50:51]
	v_lshlrev_b32_e32 v56, 16, v212
	v_and_b32_e32 v57, 0xffff0000, v212
	v_lshlrev_b32_e32 v50, 16, v213
	v_and_b32_e32 v51, 0xffff0000, v213
	v_lshlrev_b32_e32 v58, 16, v214
	v_and_b32_e32 v59, 0xffff0000, v214
	v_lshlrev_b32_e32 v52, 16, v215
	v_and_b32_e32 v53, 0xffff0000, v215
	v_pk_add_f32 v[46:47], v[46:47], v[50:51]
	v_pk_add_f32 v[44:45], v[44:45], v[56:57]
	v_pk_add_f32 v[50:51], v[42:43], v[52:53]
	v_pk_add_f32 v[52:53], v[40:41], v[58:59]
	v_cvt_pk_bf16_f32 v40, v44, v45
	v_cvt_pk_bf16_f32 v41, v46, v47
	v_cvt_pk_bf16_f32 v42, v52, v53
	v_cvt_pk_bf16_f32 v43, v50, v51
	global_store_dwordx4 v[54:55], v[40:43], off
	v_mul_f32_e32 v56, v45, v45
	v_fmac_f32_e32 v56, v44, v44
	v_fmac_f32_e32 v56, v46, v46
	v_fmac_f32_e32 v56, v47, v47
	v_fmac_f32_e32 v56, v52, v52
	v_fmac_f32_e32 v56, v53, v53
	v_fmac_f32_e32 v56, v50, v50
	v_fmac_f32_e32 v56, v51, v51
	v_lshlrev_b32_e32 v44, 16, v216
	v_and_b32_e32 v45, 0xffff0000, v216
	v_lshlrev_b32_e32 v40, 16, v217
	v_and_b32_e32 v41, 0xffff0000, v217
	v_lshlrev_b32_e32 v46, 16, v218
	v_and_b32_e32 v47, 0xffff0000, v218
	v_lshlrev_b32_e32 v42, 16, v219
	v_and_b32_e32 v43, 0xffff0000, v219
	v_pk_add_f32 v[38:39], v[38:39], v[40:41]
	v_pk_add_f32 v[36:37], v[36:37], v[44:45]
	v_pk_add_f32 v[40:41], v[34:35], v[42:43]
	v_pk_add_f32 v[42:43], v[32:33], v[46:47]
	v_cvt_pk_bf16_f32 v32, v36, v37
	v_cvt_pk_bf16_f32 v33, v38, v39
	v_cvt_pk_bf16_f32 v34, v42, v43
	v_cvt_pk_bf16_f32 v35, v40, v41
	global_store_dwordx4 v[54:55], v[32:35], off offset:256
	s_nop 1
	v_mul_f32_e32 v32, v37, v37
	v_fmac_f32_e32 v32, v36, v36
	v_fmac_f32_e32 v32, v38, v38
	v_fmac_f32_e32 v32, v39, v39
	v_fmac_f32_e32 v32, v42, v42
	v_fmac_f32_e32 v32, v43, v43
	v_fmac_f32_e32 v32, v40, v40
	v_fmac_f32_e32 v32, v41, v41
	v_add_f32_e32 v32, v56, v32
	v_mov_b32_e32 v246, v32
	v_add_u32_e32 v32, 0xa0, v140
	s_waitcnt lgkmcnt(0)
; DI float bf2f(unsigned v) { return __uint_as_float(v << 16); }
;   DI void operator()(const f32x4 (&acc)[2][2][4][2], const pg8::Unit& u, int wr, int wc, int fr_, int fq_) const {
;     ...
;             } else if (EPI == EPI_RESID) {
;               if (n == 0) {
;                 const int f8 = u.pn * 256 + bj * 128 + wc * 32 + 8 * fq;
;                 const f32x4 v1 = acc[ai][bj][m][1];
;                 f32x4 r0, r1;
;                 if (rsrc) {
;                   r0 = *(const f32x4*)(rsrc + (size_t)token * 1024 + f8); r1 = *(const f32x4*)(rsrc + (size_t)token * 1024 + f8 + 4);
;                 } else {
;                   const u32x4 xu = *(const u32x4*)(xr + (size_t)token * 1024 + f8);
;                   r0 = (f32x4){bf2f(xu.x & 0xffffu), bf2f(xu.x >> 16), bf2f(xu.y & 0xffffu), bf2f(xu.y >> 16)};
;                   r1 = (f32x4){bf2f(xu.z & 0xffffu), bf2f(xu.z >> 16), bf2f(xu.w & 0xffffu), bf2f(xu.w >> 16)};
;                 }
;                 r0 += v; r1 += v1;
;                 st_bf8(xr + (size_t)token * 1024 + f8, r0, r1, 1.f);
;                 ssq += r0[0] * r0[0] + r0[1] * r0[1] + r0[2] * r0[2] + r0[3] * r0[3] + r1[0] * r1[0] + r1[1] * r1[1] + r1[2] * r1[2] + r1[3] * r1[3];
;               }
;             } else {
;               if (n == 0) {
;                 const f32x4 v1 = acc[ai][bj][m][1];
;                 u32x4 o4;
;                 { const float t0 = fmaxf(v[0], 0.f) * rinv, t1 = fmaxf(v[1], 0.f) * rinv, t2 = fmaxf(v[2], 0.f) * rinv, t3 = fmaxf(v[3], 0.f) * rinv;
;                   o4.x = pack2(t0 * t0, t1 * t1); o4.y = pack2(t2 * t2, t3 * t3); }
;                 { const float t0 = fmaxf(v1[0], 0.f) * rinv, t1 = fmaxf(v1[1], 0.f) * rinv, t2 = fmaxf(v1[2], 0.f) * rinv, t3 = fmaxf(v1[3], 0.f) * rinv;
;                   o4.z = pack2(t0 * t0, t1 * t1); o4.w = pack2(t2 * t2, t3 * t3); }
;                 *(u32x4*)((u16*)big + (size_t)token * 4096 + u.pn * 256 + bj * 128 + wc * 32 + 8 * fq) = o4;
;               }
;             }
;           }
;         if (EPI == EPI_RESID) {
;           ssq += shx(ssq, 16, t_ & 63);
;           ssq += shx(ssq, 32, t_ & 63);
;           if (fq == 0) ss_out[(size_t)token * 16 + u.pn * 4 + wc] = ssq;
;         }
	v_ashrrev_i32_e32 v33, 31, v32
	v_lshlrev_b64 v[34:35], 11, v[32:33]
	v_lshl_add_u64 v[34:35], s[4:5], 0, v[34:35]
	v_lshl_add_u64 v[38:39], v[138:139], 1, v[34:35]
	v_lshlrev_b32_e32 v40, 16, v220
	v_and_b32_e32 v41, 0xffff0000, v220
	v_lshlrev_b32_e32 v34, 16, v221
	v_and_b32_e32 v35, 0xffff0000, v221
	v_lshlrev_b32_e32 v42, 16, v222
	v_and_b32_e32 v43, 0xffff0000, v222
	v_lshlrev_b32_e32 v36, 16, v223
	v_and_b32_e32 v37, 0xffff0000, v223
	v_pk_add_f32 v[30:31], v[30:31], v[34:35]
	v_pk_add_f32 v[28:29], v[28:29], v[40:41]
	v_pk_add_f32 v[34:35], v[26:27], v[36:37]
	v_pk_add_f32 v[36:37], v[24:25], v[42:43]
	v_cvt_pk_bf16_f32 v24, v28, v29
	v_cvt_pk_bf16_f32 v25, v30, v31
	v_cvt_pk_bf16_f32 v26, v36, v37
	v_cvt_pk_bf16_f32 v27, v34, v35
	global_store_dwordx4 v[38:39], v[24:27], off
	v_mul_f32_e32 v40, v29, v29
	v_fmac_f32_e32 v40, v28, v28
	v_fmac_f32_e32 v40, v30, v30
	v_fmac_f32_e32 v40, v31, v31
	v_fmac_f32_e32 v40, v36, v36
	v_fmac_f32_e32 v40, v37, v37
	v_fmac_f32_e32 v40, v34, v34
	v_fmac_f32_e32 v40, v35, v35
	v_lshlrev_b32_e32 v28, 16, v224
	v_and_b32_e32 v29, 0xffff0000, v224
	v_lshlrev_b32_e32 v24, 16, v225
	v_and_b32_e32 v25, 0xffff0000, v225
	v_lshlrev_b32_e32 v30, 16, v226
	v_and_b32_e32 v31, 0xffff0000, v226
	v_lshlrev_b32_e32 v26, 16, v227
	v_and_b32_e32 v27, 0xffff0000, v227
	v_pk_add_f32 v[22:23], v[22:23], v[24:25]
	v_pk_add_f32 v[20:21], v[20:21], v[28:29]
	v_pk_add_f32 v[24:25], v[18:19], v[26:27]
	v_pk_add_f32 v[26:27], v[16:17], v[30:31]
	v_cvt_pk_bf16_f32 v16, v20, v21
	v_cvt_pk_bf16_f32 v17, v22, v23
	v_cvt_pk_bf16_f32 v18, v26, v27
	v_cvt_pk_bf16_f32 v19, v24, v25
	global_store_dwordx4 v[38:39], v[16:19], off offset:256
	s_nop 1
	v_mul_f32_e32 v16, v21, v21
	v_fmac_f32_e32 v16, v20, v20
	v_fmac_f32_e32 v16, v22, v22
	v_fmac_f32_e32 v16, v23, v23
	v_fmac_f32_e32 v16, v26, v26
	v_fmac_f32_e32 v16, v27, v27
	v_fmac_f32_e32 v16, v24, v24
	v_fmac_f32_e32 v16, v25, v25
	v_add_f32_e32 v16, v40, v16
	v_mov_b32_e32 v247, v16
	v_add_u32_e32 v16, 0xb0, v140
	s_waitcnt lgkmcnt(0)
	v_ashrrev_i32_e32 v17, 31, v16
	v_lshlrev_b64 v[18:19], 11, v[16:17]
	v_lshl_add_u64 v[18:19], s[4:5], 0, v[18:19]
	v_lshl_add_u64 v[22:23], v[138:139], 1, v[18:19]
	v_lshlrev_b32_e32 v24, 16, v228
	v_and_b32_e32 v25, 0xffff0000, v228
	v_lshlrev_b32_e32 v18, 16, v229
	v_and_b32_e32 v19, 0xffff0000, v229
	v_lshlrev_b32_e32 v26, 16, v230
	v_and_b32_e32 v27, 0xffff0000, v230
	v_lshlrev_b32_e32 v20, 16, v231
	v_and_b32_e32 v21, 0xffff0000, v231
	v_pk_add_f32 v[14:15], v[14:15], v[18:19]
	v_pk_add_f32 v[12:13], v[12:13], v[24:25]
	v_pk_add_f32 v[18:19], v[10:11], v[20:21]
	v_pk_add_f32 v[20:21], v[8:9], v[26:27]
	v_cvt_pk_bf16_f32 v8, v12, v13
	v_cvt_pk_bf16_f32 v9, v14, v15
	v_cvt_pk_bf16_f32 v10, v20, v21
	v_cvt_pk_bf16_f32 v11, v18, v19
	global_store_dwordx4 v[22:23], v[8:11], off
	v_mul_f32_e32 v24, v13, v13
	v_fmac_f32_e32 v24, v12, v12
	v_fmac_f32_e32 v24, v14, v14
	v_fmac_f32_e32 v24, v15, v15
	v_fmac_f32_e32 v24, v20, v20
	v_fmac_f32_e32 v24, v21, v21
	v_fmac_f32_e32 v24, v18, v18
	v_fmac_f32_e32 v24, v19, v19
	v_lshlrev_b32_e32 v12, 16, v232
	v_and_b32_e32 v13, 0xffff0000, v232
	v_lshlrev_b32_e32 v8, 16, v233
	v_and_b32_e32 v9, 0xffff0000, v233
	v_lshlrev_b32_e32 v14, 16, v234
	v_and_b32_e32 v15, 0xffff0000, v234
	v_lshlrev_b32_e32 v10, 16, v235
	v_and_b32_e32 v11, 0xffff0000, v235
	v_pk_add_f32 v[6:7], v[6:7], v[8:9]
	v_pk_add_f32 v[4:5], v[4:5], v[12:13]
	v_pk_add_f32 v[8:9], v[2:3], v[10:11]
	v_pk_add_f32 v[10:11], v[0:1], v[14:15]
	v_cvt_pk_bf16_f32 v0, v4, v5
	v_cvt_pk_bf16_f32 v1, v6, v7
	v_cvt_pk_bf16_f32 v2, v10, v11
	v_cvt_pk_bf16_f32 v3, v8, v9
	global_store_dwordx4 v[22:23], v[0:3], off offset:256
	s_nop 1
	v_mul_f32_e32 v0, v5, v5
	v_fmac_f32_e32 v0, v4, v4
	v_fmac_f32_e32 v0, v6, v6
	v_fmac_f32_e32 v0, v7, v7
	v_fmac_f32_e32 v0, v10, v10
	v_fmac_f32_e32 v0, v11, v11
	v_fmac_f32_e32 v0, v8, v8
	v_fmac_f32_e32 v0, v9, v9
	v_add_f32_e32 v0, v24, v0
	v_mov_b32_e32 v248, v0
	ds_bpermute_b32 v158, v149, v236
	ds_bpermute_b32 v159, v149, v242
	ds_bpermute_b32 v160, v149, v243
	ds_bpermute_b32 v161, v149, v244
	ds_bpermute_b32 v162, v149, v245
	ds_bpermute_b32 v163, v149, v246
	ds_bpermute_b32 v164, v149, v247
	ds_bpermute_b32 v165, v149, v248
	s_waitcnt lgkmcnt(0)
	v_add_f32_e32 v236, v236, v158
	v_add_f32_e32 v242, v242, v159
	v_add_f32_e32 v243, v243, v160
	v_add_f32_e32 v244, v244, v161
	v_add_f32_e32 v245, v245, v162
	v_add_f32_e32 v246, v246, v163
	v_add_f32_e32 v247, v247, v164
	v_add_f32_e32 v248, v248, v165
	ds_bpermute_b32 v158, v148, v236
	ds_bpermute_b32 v159, v148, v242
	ds_bpermute_b32 v160, v148, v243
	ds_bpermute_b32 v161, v148, v244
	ds_bpermute_b32 v162, v148, v245
	ds_bpermute_b32 v163, v148, v246
	ds_bpermute_b32 v164, v148, v247
	ds_bpermute_b32 v165, v148, v248
	s_and_saveexec_b64 s[18:19], vcc
	s_cbranch_execz .LBB0_1897
	s_waitcnt lgkmcnt(0)
	v_add_f32_e32 v236, v236, v158
	v_add_f32_e32 v242, v242, v159
	v_add_f32_e32 v243, v243, v160
	v_add_f32_e32 v244, v244, v161
	v_add_f32_e32 v245, v245, v162
	v_add_f32_e32 v246, v246, v163
	v_add_f32_e32 v247, v247, v164
	v_add_f32_e32 v248, v248, v165
	v_lshlrev_b64 v[166:167], 6, v[140:141]
	v_lshl_add_u64 v[166:167], s[2:3], 0, v[166:167]
	v_lshl_add_u64 v[166:167], s[16:17], 2, v[166:167]
	s_lshl_b32 s24, s43, 2
	v_lshl_add_u64 v[166:167], v[166:167], 0, s[24:25]
	global_store_dword v[166:167], v236, off
	global_store_dword v[166:167], v242, off offset:1024
	global_store_dword v[166:167], v243, off offset:2048
	global_store_dword v[166:167], v244, off offset:3072
	s_mov_b64 vcc, 0x2000
	v_lshl_add_u64 v[166:167], v[166:167], 0, vcc
	global_store_dword v[166:167], v245, off
	global_store_dword v[166:167], v246, off offset:1024
	global_store_dword v[166:167], v247, off offset:2048
	global_store_dword v[166:167], v248, off offset:3072
	s_branch .LBB0_1897
